# 7.11 back-edge rotation: GEMM K-loop counter/pointer/exit-test block moved in front of the loop-back barrier (4 loops)
# baseline (speedup 1.0000x reference)
; #define PG8_STAGE(bufoff, gbase, voff) do { _Pragma("unroll") for (int _i = 0; _i < 2; ++_i) \
;         __builtin_amdgcn_global_load_lds((const unsigned*)((const char*)(gbase) + (voff)[_i]), (PG8_LAS unsigned*)(lds + (bufoff) + ldsw + _i * 8192), 16, 0, 0); } while (0)
; #define PG8_LDA(dst, b, h) do { _Pragma("unroll") for (int m = 0; m < 4; ++m) _Pragma("unroll") for (int k = 0; k < 2; ++k) dst[m][k] = *(const PG8_LAS bf16x8*)(lds + PG8_SA(b, h) + aoff + m * 2048 + k * 1024); } while (0)
; #define PG8_LDB(dst, b, h) do { _Pragma("unroll") for (int n = 0; n < 2; ++n) _Pragma("unroll") for (int k = 0; k < 2; ++k) dst[n][k] = *(const PG8_LAS bf16x8*)(lds + PG8_SB(b, h) + boff + n * 2048 + k * 1024); } while (0)
; #define PG8_MMA(ai, bj, At, Bt) do { __builtin_amdgcn_s_setprio(1); _Pragma("unroll") for (int m = 0; m < 4; ++m) _Pragma("unroll") for (int n = 0; n < 2; ++n) _Pragma("unroll") for (int k = 0; k < 2; ++k) \
;         acc[ai][bj][m][n] = __builtin_amdgcn_mfma_f32_16x16x32_bf16(Bt[n][k], At[m][k], acc[ai][bj][m][n], 0, 0, 0); __builtin_amdgcn_s_setprio(0); } while (0)
; #define PG8_WAIT_V(n) asm volatile("s_waitcnt vmcnt(" #n ")" ::: "memory")
; #define PG8_WAIT_L(n) asm volatile("s_waitcnt lgkmcnt(" #n ")" ::: "memory")
; #define PG8_BAR __builtin_amdgcn_s_barrier()
; #define PG8_SCHED __builtin_amdgcn_sched_barrier(0)
; template <class Epi, class Sched, bool ALIGN_EPI = false, bool SP2 = false>
; __device__ __forceinline__ void gemm_phase(PG8_LAS unsigned char* lds, const Gemm g, const Sched S, const Epi E) {
;     ...
;             PG8_LDB(B0, 0, 0); PG8_LDB(B1, 0, 1); PG8_SCHED; PG8_LDA(At, 0, 0); PG8_STAGE(PG8_SA(1, 1), a1 + hstep, voffA);
;             PG8_WAIT_V(8); PG8_WAIT_L(0); PG8_BAR; PG8_MMA(0, 0, At, B0); PG8_MMA(0, 1, At, B1); PG8_BAR; PG8_SCHED;
;             PG8_LDA(At, 0, 1); PG8_STAGE(PG8_SB(0, 0), b2, voffB); PG8_STAGE(PG8_SB(0, 1), b2 + hstep, voffB); PG8_STAGE(PG8_SA(0, 0), a2, voffA);
;             PG8_WAIT_V(8); PG8_WAIT_L(0); PG8_BAR; PG8_MMA(1, 0, At, B0); PG8_MMA(1, 1, At, B1); PG8_BAR; PG8_SCHED;
;             PG8_LDB(B0, 1, 0); PG8_LDB(B1, 1, 1); PG8_SCHED; PG8_LDA(At, 1, 0); PG8_STAGE(PG8_SA(0, 1), a2 + hstep, voffA);
;             PG8_WAIT_V(8); PG8_WAIT_L(0); PG8_BAR; PG8_MMA(0, 0, At, B0); PG8_MMA(0, 1, At, B1); PG8_BAR; PG8_SCHED;
.LBB0_180:
	s_add_i32 s20, s18, 2
	s_add_u32 s21, s16, 0x80
	s_addc_u32 s19, s17, 0
	s_add_i32 s25, 0, 0x10000
	s_cmp_eq_u32 s75, s18
	s_cselect_b32 s19, s1, s19
	s_cselect_b32 s18, s0, s21
	v_add_u32_e32 v140, s25, v143
	s_cselect_b32 s23, s59, s15
	s_cselect_b32 s22, s58, s14
	s_add_i32 s21, 0, 0x14000
	ds_read_b128 v[154:157], v140
	ds_read_b128 v[158:161], v140 offset:1024
	ds_read_b128 v[162:165], v140 offset:2048
	ds_read_b128 v[166:169], v140 offset:3072
	v_add_u32_e32 v140, s21, v143
	ds_read_b128 v[170:173], v140
	ds_read_b128 v[174:177], v140 offset:1024
	ds_read_b128 v[182:185], v140 offset:2048
	ds_read_b128 v[198:201], v140 offset:3072
	v_lshl_add_u64 v[140:141], s[16:17], 0, v[136:137]
	s_add_i32 m0, s68, 0xc000
	ds_read_b128 v[202:205], v146
	ds_read_b128 v[206:209], v146 offset:1024
	ds_read_b128 v[210:213], v146 offset:2048
	ds_read_b128 v[214:217], v146 offset:3072
	ds_read_b128 v[218:221], v146 offset:4096
	ds_read_b128 v[222:225], v146 offset:5120
	ds_read_b128 v[226:229], v146 offset:6144
	ds_read_b128 v[230:233], v146 offset:7168
	global_load_lds_dwordx4 v[140:141], off
	v_lshl_add_u64 v[140:141], s[16:17], 0, v[138:139]
	s_add_i32 m0, s68, 0xe000
	s_nop 0
	global_load_lds_dwordx4 v[140:141], off
	s_waitcnt vmcnt(8)
	s_waitcnt lgkmcnt(0)
	s_barrier
	s_setprio 1
	s_waitcnt lgkmcnt(0)
	v_mfma_f32_16x16x32_bf16 v[126:129], v[154:157], v[202:205], v[126:129]
	v_mfma_f32_16x16x32_bf16 v[118:121], v[162:165], v[202:205], v[118:121]
	v_mfma_f32_16x16x32_bf16 v[110:113], v[154:157], v[210:213], v[110:113]
	v_mfma_f32_16x16x32_bf16 v[102:105], v[162:165], v[210:213], v[102:105]
	v_mfma_f32_16x16x32_bf16 v[94:97], v[154:157], v[218:221], v[94:97]
	v_mfma_f32_16x16x32_bf16 v[86:89], v[162:165], v[218:221], v[86:89]
	v_mfma_f32_16x16x32_bf16 v[78:81], v[154:157], v[226:229], v[78:81]
	v_mfma_f32_16x16x32_bf16 v[70:73], v[162:165], v[226:229], v[70:73]
	v_mfma_f32_16x16x32_bf16 v[126:129], v[158:161], v[206:209], v[126:129]
	v_mfma_f32_16x16x32_bf16 v[118:121], v[166:169], v[206:209], v[118:121]
	v_mfma_f32_16x16x32_bf16 v[110:113], v[158:161], v[214:217], v[110:113]
	v_mfma_f32_16x16x32_bf16 v[102:105], v[166:169], v[214:217], v[102:105]
	v_mfma_f32_16x16x32_bf16 v[94:97], v[158:161], v[222:225], v[94:97]
	v_mfma_f32_16x16x32_bf16 v[86:89], v[166:169], v[222:225], v[86:89]
	v_mfma_f32_16x16x32_bf16 v[78:81], v[158:161], v[230:233], v[78:81]
	v_mfma_f32_16x16x32_bf16 v[70:73], v[166:169], v[230:233], v[70:73]
	s_setprio 0
	s_setprio 1
	v_mfma_f32_16x16x32_bf16 v[122:125], v[170:173], v[202:205], v[122:125]
	v_mfma_f32_16x16x32_bf16 v[114:117], v[182:185], v[202:205], v[114:117]
	v_mfma_f32_16x16x32_bf16 v[106:109], v[170:173], v[210:213], v[106:109]
	v_mfma_f32_16x16x32_bf16 v[98:101], v[182:185], v[210:213], v[98:101]
	v_mfma_f32_16x16x32_bf16 v[90:93], v[170:173], v[218:221], v[90:93]
	v_mfma_f32_16x16x32_bf16 v[82:85], v[182:185], v[218:221], v[82:85]
	v_mfma_f32_16x16x32_bf16 v[74:77], v[170:173], v[226:229], v[74:77]
	v_mfma_f32_16x16x32_bf16 v[66:69], v[182:185], v[226:229], v[66:69]
	v_mfma_f32_16x16x32_bf16 v[122:125], v[174:177], v[206:209], v[122:125]
	v_mfma_f32_16x16x32_bf16 v[114:117], v[198:201], v[206:209], v[114:117]
	v_mfma_f32_16x16x32_bf16 v[106:109], v[174:177], v[214:217], v[106:109]
	v_mfma_f32_16x16x32_bf16 v[98:101], v[198:201], v[214:217], v[98:101]
	v_mfma_f32_16x16x32_bf16 v[90:93], v[174:177], v[222:225], v[90:93]
	v_mfma_f32_16x16x32_bf16 v[82:85], v[198:201], v[222:225], v[82:85]
	v_mfma_f32_16x16x32_bf16 v[74:77], v[174:177], v[230:233], v[74:77]
	v_mfma_f32_16x16x32_bf16 v[66:69], v[198:201], v[230:233], v[66:69]
	s_setprio 0
	s_barrier
	s_add_i32 s25, s25, s61
	v_lshl_add_u64 v[140:141], s[22:23], 0, v[0:1]
	s_mov_b32 m0, s25
	ds_read_b128 v[202:205], v146 offset:16384
	ds_read_b128 v[206:209], v146 offset:17408
	ds_read_b128 v[210:213], v146 offset:18432
	ds_read_b128 v[214:217], v146 offset:19456
	ds_read_b128 v[218:221], v146 offset:20480
	ds_read_b128 v[222:225], v146 offset:21504
	ds_read_b128 v[226:229], v146 offset:22528
	ds_read_b128 v[230:233], v146 offset:23552
	global_load_lds_dwordx4 v[140:141], off
	s_add_i32 m0, s25, 0x2000
	v_lshl_add_u64 v[234:235], s[22:23], 0, v[130:131]
	s_add_u32 s22, s22, s28
	s_addc_u32 s23, s23, 0
	s_add_i32 s21, s21, s61
	global_load_lds_dwordx4 v[234:235], off
	v_lshl_add_u64 v[236:237], s[22:23], 0, v[0:1]
	s_mov_b32 m0, s21
	v_lshl_add_u64 v[238:239], s[22:23], 0, v[130:131]
	global_load_lds_dwordx4 v[236:237], off
	s_add_i32 m0, s21, 0x2000
	v_lshl_add_u64 v[240:241], s[18:19], 0, v[134:135]
	global_load_lds_dwordx4 v[238:239], off
	s_mov_b32 m0, s68
	v_lshl_add_u64 v[242:243], s[18:19], 0, v[132:133]
	global_load_lds_dwordx4 v[240:241], off
	s_mov_b32 m0, s69
	s_nop 0
	global_load_lds_dwordx4 v[242:243], off
	s_waitcnt vmcnt(8)
	s_waitcnt lgkmcnt(0)
	s_barrier
; #define PG8_STAGE(bufoff, gbase, voff) do { _Pragma("unroll") for (int _i = 0; _i < 2; ++_i) \
;         __builtin_amdgcn_global_load_lds((const unsigned*)((const char*)(gbase) + (voff)[_i]), (PG8_LAS unsigned*)(lds + (bufoff) + ldsw + _i * 8192), 16, 0, 0); } while (0)
; #define PG8_LDA(dst, b, h) do { _Pragma("unroll") for (int m = 0; m < 4; ++m) _Pragma("unroll") for (int k = 0; k < 2; ++k) dst[m][k] = *(const PG8_LAS bf16x8*)(lds + PG8_SA(b, h) + aoff + m * 2048 + k * 1024); } while (0)
; #define PG8_LDB(dst, b, h) do { _Pragma("unroll") for (int n = 0; n < 2; ++n) _Pragma("unroll") for (int k = 0; k < 2; ++k) dst[n][k] = *(const PG8_LAS bf16x8*)(lds + PG8_SB(b, h) + boff + n * 2048 + k * 1024); } while (0)
; #define PG8_MMA(ai, bj, At, Bt) do { __builtin_amdgcn_s_setprio(1); _Pragma("unroll") for (int m = 0; m < 4; ++m) _Pragma("unroll") for (int n = 0; n < 2; ++n) _Pragma("unroll") for (int k = 0; k < 2; ++k) \
;         acc[ai][bj][m][n] = __builtin_amdgcn_mfma_f32_16x16x32_bf16(Bt[n][k], At[m][k], acc[ai][bj][m][n], 0, 0, 0); __builtin_amdgcn_s_setprio(0); } while (0)
; #define PG8_WAIT_V(n) asm volatile("s_waitcnt vmcnt(" #n ")" ::: "memory")
; #define PG8_WAIT_L(n) asm volatile("s_waitcnt lgkmcnt(" #n ")" ::: "memory")
; #define PG8_BAR __builtin_amdgcn_s_barrier()
; #define PG8_SCHED __builtin_amdgcn_sched_barrier(0)
; template <class Epi, class Sched, bool ALIGN_EPI = false, bool SP2 = false>
; __device__ __forceinline__ void gemm_phase(PG8_LAS unsigned char* lds, const Gemm g, const Sched S, const Epi E) {
;     ...
;             PG8_WAIT_V(8); PG8_WAIT_L(0); PG8_BAR; PG8_MMA(1, 0, At, B0); PG8_MMA(1, 1, At, B1); PG8_BAR; PG8_SCHED;
;             PG8_LDB(B0, 1, 0); PG8_LDB(B1, 1, 1); PG8_SCHED; PG8_LDA(At, 1, 0); PG8_STAGE(PG8_SA(0, 1), a2 + hstep, voffA);
;             PG8_WAIT_V(8); PG8_WAIT_L(0); PG8_BAR; PG8_MMA(0, 0, At, B0); PG8_MMA(0, 1, At, B1); PG8_BAR; PG8_SCHED;
	s_setprio 1
	s_waitcnt lgkmcnt(0)
	v_mfma_f32_16x16x32_bf16 v[62:65], v[154:157], v[202:205], v[62:65]
	v_mfma_f32_16x16x32_bf16 v[54:57], v[162:165], v[202:205], v[54:57]
	v_mfma_f32_16x16x32_bf16 v[46:49], v[154:157], v[210:213], v[46:49]
	v_mfma_f32_16x16x32_bf16 v[38:41], v[162:165], v[210:213], v[38:41]
	v_mfma_f32_16x16x32_bf16 v[30:33], v[154:157], v[218:221], v[30:33]
	v_mfma_f32_16x16x32_bf16 v[22:25], v[162:165], v[218:221], v[22:25]
	v_mfma_f32_16x16x32_bf16 v[14:17], v[154:157], v[226:229], v[14:17]
	v_mfma_f32_16x16x32_bf16 v[6:9], v[162:165], v[226:229], v[6:9]
	v_mfma_f32_16x16x32_bf16 v[62:65], v[158:161], v[206:209], v[62:65]
	v_mfma_f32_16x16x32_bf16 v[54:57], v[166:169], v[206:209], v[54:57]
	v_mfma_f32_16x16x32_bf16 v[46:49], v[158:161], v[214:217], v[46:49]
	v_mfma_f32_16x16x32_bf16 v[38:41], v[166:169], v[214:217], v[38:41]
	v_mfma_f32_16x16x32_bf16 v[30:33], v[158:161], v[222:225], v[30:33]
	v_mfma_f32_16x16x32_bf16 v[22:25], v[166:169], v[222:225], v[22:25]
	v_mfma_f32_16x16x32_bf16 v[14:17], v[158:161], v[230:233], v[14:17]
	v_mfma_f32_16x16x32_bf16 v[6:9], v[166:169], v[230:233], v[6:9]
	s_setprio 0
	s_setprio 1
	v_mfma_f32_16x16x32_bf16 v[58:61], v[170:173], v[202:205], v[58:61]
	v_mfma_f32_16x16x32_bf16 v[50:53], v[182:185], v[202:205], v[50:53]
	v_mfma_f32_16x16x32_bf16 v[42:45], v[170:173], v[210:213], v[42:45]
	v_mfma_f32_16x16x32_bf16 v[34:37], v[182:185], v[210:213], v[34:37]
	v_mfma_f32_16x16x32_bf16 v[26:29], v[170:173], v[218:221], v[26:29]
	v_mfma_f32_16x16x32_bf16 v[18:21], v[182:185], v[218:221], v[18:21]
	v_mfma_f32_16x16x32_bf16 v[10:13], v[170:173], v[226:229], v[10:13]
	v_mfma_f32_16x16x32_bf16 v[2:5], v[182:185], v[226:229], v[2:5]
	v_mfma_f32_16x16x32_bf16 v[58:61], v[174:177], v[206:209], v[58:61]
	v_mfma_f32_16x16x32_bf16 v[50:53], v[198:201], v[206:209], v[50:53]
	v_mfma_f32_16x16x32_bf16 v[42:45], v[174:177], v[214:217], v[42:45]
	v_mfma_f32_16x16x32_bf16 v[34:37], v[198:201], v[214:217], v[34:37]
	v_mfma_f32_16x16x32_bf16 v[26:29], v[174:177], v[222:225], v[26:29]
	v_mfma_f32_16x16x32_bf16 v[18:21], v[198:201], v[222:225], v[18:21]
	v_mfma_f32_16x16x32_bf16 v[10:13], v[174:177], v[230:233], v[10:13]
	v_mfma_f32_16x16x32_bf16 v[2:5], v[198:201], v[230:233], v[2:5]
	s_setprio 0
	s_barrier
	s_add_i32 s21, 0, 0x18000
	s_add_i32 s22, 0, 0x1c000
	v_add_u32_e32 v166, s21, v143
	v_add_u32_e32 v186, s22, v143
	ds_read_b128 v[154:157], v166
	ds_read_b128 v[158:161], v166 offset:1024
	ds_read_b128 v[162:165], v166 offset:2048
	ds_read_b128 v[166:169], v166 offset:3072
	ds_read_b128 v[170:173], v186
	ds_read_b128 v[174:177], v186 offset:1024
	ds_read_b128 v[182:185], v186 offset:2048
	ds_read_b128 v[198:201], v186 offset:3072
	s_add_u32 s18, s18, s28
	s_addc_u32 s19, s19, 0
	s_mov_b32 m0, s70
	v_lshl_add_u64 v[244:245], s[18:19], 0, v[134:135]
	ds_read_b128 v[202:205], v146 offset:32768
	ds_read_b128 v[206:209], v146 offset:33792
	ds_read_b128 v[210:213], v146 offset:34816
	ds_read_b128 v[214:217], v146 offset:35840
	ds_read_b128 v[218:221], v146 offset:36864
	ds_read_b128 v[222:225], v146 offset:37888
	ds_read_b128 v[226:229], v146 offset:38912
	ds_read_b128 v[230:233], v146 offset:39936
	global_load_lds_dwordx4 v[244:245], off
	v_lshl_add_u64 v[244:245], s[18:19], 0, v[132:133]
	s_mov_b32 m0, s71
	s_nop 0
	global_load_lds_dwordx4 v[244:245], off
	s_waitcnt vmcnt(8)
	s_waitcnt lgkmcnt(0)
	s_barrier
	s_setprio 1
	s_waitcnt lgkmcnt(0)
	v_mfma_f32_16x16x32_bf16 v[126:129], v[154:157], v[202:205], v[126:129]
	v_mfma_f32_16x16x32_bf16 v[118:121], v[162:165], v[202:205], v[118:121]
	v_mfma_f32_16x16x32_bf16 v[110:113], v[154:157], v[210:213], v[110:113]
	v_mfma_f32_16x16x32_bf16 v[102:105], v[162:165], v[210:213], v[102:105]
	v_mfma_f32_16x16x32_bf16 v[94:97], v[154:157], v[218:221], v[94:97]
	v_mfma_f32_16x16x32_bf16 v[86:89], v[162:165], v[218:221], v[86:89]
	v_mfma_f32_16x16x32_bf16 v[78:81], v[154:157], v[226:229], v[78:81]
	v_mfma_f32_16x16x32_bf16 v[70:73], v[162:165], v[226:229], v[70:73]
	v_mfma_f32_16x16x32_bf16 v[126:129], v[158:161], v[206:209], v[126:129]
	v_mfma_f32_16x16x32_bf16 v[118:121], v[166:169], v[206:209], v[118:121]
	v_mfma_f32_16x16x32_bf16 v[110:113], v[158:161], v[214:217], v[110:113]
	v_mfma_f32_16x16x32_bf16 v[102:105], v[166:169], v[214:217], v[102:105]
	v_mfma_f32_16x16x32_bf16 v[94:97], v[158:161], v[222:225], v[94:97]
	v_mfma_f32_16x16x32_bf16 v[86:89], v[166:169], v[222:225], v[86:89]
	v_mfma_f32_16x16x32_bf16 v[78:81], v[158:161], v[230:233], v[78:81]
	v_mfma_f32_16x16x32_bf16 v[70:73], v[166:169], v[230:233], v[70:73]
	s_setprio 0
	s_setprio 1
	v_mfma_f32_16x16x32_bf16 v[122:125], v[170:173], v[202:205], v[122:125]
	v_mfma_f32_16x16x32_bf16 v[114:117], v[182:185], v[202:205], v[114:117]
	v_mfma_f32_16x16x32_bf16 v[106:109], v[170:173], v[210:213], v[106:109]
	v_mfma_f32_16x16x32_bf16 v[98:101], v[182:185], v[210:213], v[98:101]
	v_mfma_f32_16x16x32_bf16 v[90:93], v[170:173], v[218:221], v[90:93]
	v_mfma_f32_16x16x32_bf16 v[82:85], v[182:185], v[218:221], v[82:85]
	v_mfma_f32_16x16x32_bf16 v[74:77], v[170:173], v[226:229], v[74:77]
	v_mfma_f32_16x16x32_bf16 v[66:69], v[182:185], v[226:229], v[66:69]
	v_mfma_f32_16x16x32_bf16 v[122:125], v[174:177], v[206:209], v[122:125]
	v_mfma_f32_16x16x32_bf16 v[114:117], v[198:201], v[206:209], v[114:117]
	v_mfma_f32_16x16x32_bf16 v[106:109], v[174:177], v[214:217], v[106:109]
	v_mfma_f32_16x16x32_bf16 v[98:101], v[198:201], v[214:217], v[98:101]
	v_mfma_f32_16x16x32_bf16 v[90:93], v[174:177], v[222:225], v[90:93]
	v_mfma_f32_16x16x32_bf16 v[82:85], v[198:201], v[222:225], v[82:85]
	v_mfma_f32_16x16x32_bf16 v[74:77], v[174:177], v[230:233], v[74:77]
	v_mfma_f32_16x16x32_bf16 v[66:69], v[198:201], v[230:233], v[66:69]
	s_setprio 0
	s_barrier
; #define PG8_STAGE(bufoff, gbase, voff) do { _Pragma("unroll") for (int _i = 0; _i < 2; ++_i) \
;         __builtin_amdgcn_global_load_lds((const unsigned*)((const char*)(gbase) + (voff)[_i]), (PG8_LAS unsigned*)(lds + (bufoff) + ldsw + _i * 8192), 16, 0, 0); } while (0)
; #define PG8_LDA(dst, b, h) do { _Pragma("unroll") for (int m = 0; m < 4; ++m) _Pragma("unroll") for (int k = 0; k < 2; ++k) dst[m][k] = *(const PG8_LAS bf16x8*)(lds + PG8_SA(b, h) + aoff + m * 2048 + k * 1024); } while (0)
; #define PG8_MMA(ai, bj, At, Bt) do { __builtin_amdgcn_s_setprio(1); _Pragma("unroll") for (int m = 0; m < 4; ++m) _Pragma("unroll") for (int n = 0; n < 2; ++n) _Pragma("unroll") for (int k = 0; k < 2; ++k) \
;         acc[ai][bj][m][n] = __builtin_amdgcn_mfma_f32_16x16x32_bf16(Bt[n][k], At[m][k], acc[ai][bj][m][n], 0, 0, 0); __builtin_amdgcn_s_setprio(0); } while (0)
; #define PG8_WAIT_V(n) asm volatile("s_waitcnt vmcnt(" #n ")" ::: "memory")
; #define PG8_WAIT_L(n) asm volatile("s_waitcnt lgkmcnt(" #n ")" ::: "memory")
; #define PG8_BAR __builtin_amdgcn_s_barrier()
; #define PG8_SCHED __builtin_amdgcn_sched_barrier(0)
; template <class Epi, class Sched, bool ALIGN_EPI = false, bool SP2 = false>
; __device__ __forceinline__ void gemm_phase(PG8_LAS unsigned char* lds, const Gemm g, const Sched S, const Epi E) {
;     ...
;         for (int t = 0; t < nt; t += 2) {
;             const bool last = (t == nt - 2);
;             const char* a1 = cA + (size_t)(t + 1) * kstep;
;             const char* a2 = last ? nA : cA + (size_t)(t + 2) * kstep; const char* b2 = last ? nB : cB + (size_t)(t + 2) * kstep;
;     ...
;             PG8_LDA(At, 1, 1); PG8_STAGE(PG8_SB(1, 0), b3, voffB); PG8_STAGE(PG8_SB(1, 1), b3 + hstep, voffB); PG8_STAGE(PG8_SA(1, 0), a3, voffA);
;             PG8_WAIT_V(8); PG8_WAIT_L(0); PG8_BAR; PG8_MMA(1, 0, At, B0); PG8_MMA(1, 1, At, B1); PG8_BAR; PG8_SCHED;
	s_add_i32 s18, s21, s61
	v_lshl_add_u64 v[140:141], v[140:141], 0, s[12:13]
	s_mov_b32 m0, s18
	ds_read_b128 v[202:205], v146 offset:49152
	ds_read_b128 v[206:209], v146 offset:50176
	ds_read_b128 v[210:213], v146 offset:51200
	ds_read_b128 v[214:217], v146 offset:52224
	ds_read_b128 v[218:221], v146 offset:53248
	ds_read_b128 v[222:225], v146 offset:54272
	ds_read_b128 v[226:229], v146 offset:55296
	ds_read_b128 v[230:233], v146 offset:56320
	global_load_lds_dwordx4 v[140:141], off
	v_lshl_add_u64 v[140:141], v[234:235], 0, s[12:13]
	s_add_i32 m0, s18, 0x2000
	s_add_i32 s18, s22, s61
	global_load_lds_dwordx4 v[140:141], off
	v_lshl_add_u64 v[140:141], v[236:237], 0, s[12:13]
	s_mov_b32 m0, s18
	s_nop 0
	global_load_lds_dwordx4 v[140:141], off
	v_lshl_add_u64 v[140:141], v[238:239], 0, s[12:13]
	s_add_i32 m0, s18, 0x2000
	s_nop 0
	global_load_lds_dwordx4 v[140:141], off
	v_lshl_add_u64 v[140:141], v[240:241], 0, s[12:13]
	s_mov_b32 m0, s73
	s_nop 0
	global_load_lds_dwordx4 v[140:141], off
	v_lshl_add_u64 v[140:141], v[242:243], 0, s[12:13]
	s_mov_b32 m0, s74
	s_nop 0
	global_load_lds_dwordx4 v[140:141], off
	s_waitcnt vmcnt(8)
	s_waitcnt lgkmcnt(0)
	s_barrier
	s_setprio 1
	s_waitcnt lgkmcnt(0)
	v_mfma_f32_16x16x32_bf16 v[62:65], v[154:157], v[202:205], v[62:65]
	v_mfma_f32_16x16x32_bf16 v[54:57], v[162:165], v[202:205], v[54:57]
	v_mfma_f32_16x16x32_bf16 v[46:49], v[154:157], v[210:213], v[46:49]
	v_mfma_f32_16x16x32_bf16 v[38:41], v[162:165], v[210:213], v[38:41]
	v_mfma_f32_16x16x32_bf16 v[30:33], v[154:157], v[218:221], v[30:33]
	v_mfma_f32_16x16x32_bf16 v[22:25], v[162:165], v[218:221], v[22:25]
	v_mfma_f32_16x16x32_bf16 v[14:17], v[154:157], v[226:229], v[14:17]
	v_mfma_f32_16x16x32_bf16 v[6:9], v[162:165], v[226:229], v[6:9]
	v_mfma_f32_16x16x32_bf16 v[62:65], v[158:161], v[206:209], v[62:65]
	v_mfma_f32_16x16x32_bf16 v[54:57], v[166:169], v[206:209], v[54:57]
	v_mfma_f32_16x16x32_bf16 v[46:49], v[158:161], v[214:217], v[46:49]
	v_mfma_f32_16x16x32_bf16 v[38:41], v[166:169], v[214:217], v[38:41]
	v_mfma_f32_16x16x32_bf16 v[30:33], v[158:161], v[222:225], v[30:33]
	v_mfma_f32_16x16x32_bf16 v[22:25], v[166:169], v[222:225], v[22:25]
	v_mfma_f32_16x16x32_bf16 v[14:17], v[158:161], v[230:233], v[14:17]
	v_mfma_f32_16x16x32_bf16 v[6:9], v[166:169], v[230:233], v[6:9]
	s_setprio 0
	s_setprio 1
	v_mfma_f32_16x16x32_bf16 v[58:61], v[170:173], v[202:205], v[58:61]
	v_mfma_f32_16x16x32_bf16 v[50:53], v[182:185], v[202:205], v[50:53]
	v_mfma_f32_16x16x32_bf16 v[42:45], v[170:173], v[210:213], v[42:45]
	v_mfma_f32_16x16x32_bf16 v[34:37], v[182:185], v[210:213], v[34:37]
	v_mfma_f32_16x16x32_bf16 v[26:29], v[170:173], v[218:221], v[26:29]
	v_mfma_f32_16x16x32_bf16 v[18:21], v[182:185], v[218:221], v[18:21]
	v_mfma_f32_16x16x32_bf16 v[10:13], v[170:173], v[226:229], v[10:13]
	v_mfma_f32_16x16x32_bf16 v[2:5], v[182:185], v[226:229], v[2:5]
	v_mfma_f32_16x16x32_bf16 v[58:61], v[174:177], v[206:209], v[58:61]
	v_mfma_f32_16x16x32_bf16 v[50:53], v[198:201], v[206:209], v[50:53]
	v_mfma_f32_16x16x32_bf16 v[42:45], v[174:177], v[214:217], v[42:45]
	v_mfma_f32_16x16x32_bf16 v[34:37], v[198:201], v[214:217], v[34:37]
	v_mfma_f32_16x16x32_bf16 v[26:29], v[174:177], v[222:225], v[26:29]
	v_mfma_f32_16x16x32_bf16 v[18:21], v[198:201], v[222:225], v[18:21]
	v_mfma_f32_16x16x32_bf16 v[10:13], v[174:177], v[230:233], v[10:13]
	v_mfma_f32_16x16x32_bf16 v[2:5], v[198:201], v[230:233], v[2:5]
	s_setprio 0
	s_add_u32 s16, s16, 0x100
	s_addc_u32 s17, s17, 0
	s_add_u32 s14, s14, 0x100
	s_addc_u32 s15, s15, 0
	s_cmp_ge_u32 s20, s72
	s_mov_b32 s18, s20
	s_barrier
	s_cbranch_scc0 .LBB0_180
	s_and_b64 vcc, exec, s[56:57]
	s_cbranch_vccz .LBB0_183
	s_barrier

; #define PG8_STAGE(bufoff, gbase, voff) do { _Pragma("unroll") for (int _i = 0; _i < 2; ++_i) \
;         __builtin_amdgcn_global_load_lds((const unsigned*)((const char*)(gbase) + (voff)[_i]), (PG8_LAS unsigned*)(lds + (bufoff) + ldsw + _i * 8192), 16, 0, 0); } while (0)
; #define PG8_LDA(dst, b, h) do { _Pragma("unroll") for (int m = 0; m < 4; ++m) _Pragma("unroll") for (int k = 0; k < 2; ++k) dst[m][k] = *(const PG8_LAS bf16x8*)(lds + PG8_SA(b, h) + aoff + m * 2048 + k * 1024); } while (0)
; #define PG8_LDB(dst, b, h) do { _Pragma("unroll") for (int n = 0; n < 2; ++n) _Pragma("unroll") for (int k = 0; k < 2; ++k) dst[n][k] = *(const PG8_LAS bf16x8*)(lds + PG8_SB(b, h) + boff + n * 2048 + k * 1024); } while (0)
; #define PG8_MMA(ai, bj, At, Bt) do { __builtin_amdgcn_s_setprio(1); _Pragma("unroll") for (int m = 0; m < 4; ++m) _Pragma("unroll") for (int n = 0; n < 2; ++n) _Pragma("unroll") for (int k = 0; k < 2; ++k) \
;         acc[ai][bj][m][n] = __builtin_amdgcn_mfma_f32_16x16x32_bf16(Bt[n][k], At[m][k], acc[ai][bj][m][n], 0, 0, 0); __builtin_amdgcn_s_setprio(0); } while (0)
; #define PG8_WAIT_V(n) asm volatile("s_waitcnt vmcnt(" #n ")" ::: "memory")
; #define PG8_WAIT_L(n) asm volatile("s_waitcnt lgkmcnt(" #n ")" ::: "memory")
; #define PG8_BAR __builtin_amdgcn_s_barrier()
; #define PG8_SCHED __builtin_amdgcn_sched_barrier(0)
; template <class Epi, class Sched, bool ALIGN_EPI = false, bool SP2 = false>
; __device__ __forceinline__ void gemm_phase(PG8_LAS unsigned char* lds, const Gemm g, const Sched S, const Epi E) {
;     ...
;             const bool last = (t == nt - 2);
;             const char* a1 = cA + (size_t)(t + 1) * kstep;
;             const char* a2 = last ? nA : cA + (size_t)(t + 2) * kstep; const char* b2 = last ? nB : cB + (size_t)(t + 2) * kstep;
;             const char* a3 = a2 + kstep; const char* b3 = b2 + kstep;
;             if (last && has_next) S.a_ready(nxt);
;             if constexpr (SP2) {
;             PG8_LDB(B0, 0, 0); PG8_LDB(B1, 0, 1); PG8_SCHED; PG8_LDA(At, 0, 0); PG8_STAGE(PG8_SA(1, 1), a1 + hstep, voffA);
;             PG8_WAIT_V(8); PG8_WAIT_L(0); PG8_BAR; PG8_MMA(0, 0, At, B0); PG8_MMA(0, 1, At, B1); PG8_BAR; PG8_SCHED;
;             PG8_LDA(At, 0, 1); PG8_STAGE(PG8_SB(0, 0), b2, voffB); PG8_STAGE(PG8_SB(0, 1), b2 + hstep, voffB); PG8_STAGE(PG8_SA(0, 0), a2, voffA);
.LBB0_224:
	s_add_i32 s21, s20, 2
	s_add_u32 s22, s30, 0x80
	s_addc_u32 s23, s31, 0
	s_add_i32 s26, 0, 0x10000
	s_cmp_eq_u32 s81, s20
	s_cselect_b32 s75, s1, s23
	s_cselect_b32 s74, s0, s22
	v_add_u32_e32 v141, s26, v147
	s_cselect_b32 s23, s19, s15
	s_cselect_b32 s22, s18, s14
	s_add_i32 s20, 0, 0x14000
	ds_read_b128 v[154:157], v141
	ds_read_b128 v[158:161], v141 offset:1024
	ds_read_b128 v[162:165], v141 offset:2048
	ds_read_b128 v[166:169], v141 offset:3072
	v_add_u32_e32 v141, s20, v147
	ds_read_b128 v[170:173], v141
	ds_read_b128 v[174:177], v141 offset:1024
	ds_read_b128 v[182:185], v141 offset:2048
	ds_read_b128 v[198:201], v141 offset:3072
	v_lshl_add_u64 v[234:235], s[30:31], 0, v[136:137]
	s_add_i32 m0, s85, 0xc000
	ds_read_b128 v[202:205], v152
	ds_read_b128 v[206:209], v152 offset:1024
	ds_read_b128 v[210:213], v152 offset:2048
	ds_read_b128 v[214:217], v152 offset:3072
	ds_read_b128 v[218:221], v152 offset:4096
	ds_read_b128 v[222:225], v152 offset:5120
	ds_read_b128 v[226:229], v152 offset:6144
	ds_read_b128 v[230:233], v152 offset:7168
	global_load_lds_dwordx4 v[234:235], off
	v_lshl_add_u64 v[234:235], s[30:31], 0, v[138:139]
	s_add_i32 m0, s85, 0xe000
	s_nop 0
	global_load_lds_dwordx4 v[234:235], off
	s_waitcnt vmcnt(8)
	s_waitcnt lgkmcnt(0)
	s_barrier
	s_setprio 1
	s_waitcnt lgkmcnt(0)
	v_mfma_f32_16x16x32_bf16 v[126:129], v[154:157], v[202:205], v[126:129]
	v_mfma_f32_16x16x32_bf16 v[122:125], v[162:165], v[202:205], v[122:125]
	v_mfma_f32_16x16x32_bf16 v[110:113], v[154:157], v[210:213], v[110:113]
	v_mfma_f32_16x16x32_bf16 v[106:109], v[162:165], v[210:213], v[106:109]
	v_mfma_f32_16x16x32_bf16 v[94:97], v[154:157], v[218:221], v[94:97]
	v_mfma_f32_16x16x32_bf16 v[90:93], v[162:165], v[218:221], v[90:93]
	v_mfma_f32_16x16x32_bf16 v[78:81], v[154:157], v[226:229], v[78:81]
	v_mfma_f32_16x16x32_bf16 v[74:77], v[162:165], v[226:229], v[74:77]
	v_mfma_f32_16x16x32_bf16 v[126:129], v[158:161], v[206:209], v[126:129]
	v_mfma_f32_16x16x32_bf16 v[122:125], v[166:169], v[206:209], v[122:125]
	v_mfma_f32_16x16x32_bf16 v[110:113], v[158:161], v[214:217], v[110:113]
	v_mfma_f32_16x16x32_bf16 v[106:109], v[166:169], v[214:217], v[106:109]
	v_mfma_f32_16x16x32_bf16 v[94:97], v[158:161], v[222:225], v[94:97]
	v_mfma_f32_16x16x32_bf16 v[90:93], v[166:169], v[222:225], v[90:93]
	v_mfma_f32_16x16x32_bf16 v[78:81], v[158:161], v[230:233], v[78:81]
	v_mfma_f32_16x16x32_bf16 v[74:77], v[166:169], v[230:233], v[74:77]
	s_setprio 0
	s_setprio 1
	v_mfma_f32_16x16x32_bf16 v[118:121], v[170:173], v[202:205], v[118:121]
	v_mfma_f32_16x16x32_bf16 v[114:117], v[182:185], v[202:205], v[114:117]
	v_mfma_f32_16x16x32_bf16 v[102:105], v[170:173], v[210:213], v[102:105]
	v_mfma_f32_16x16x32_bf16 v[98:101], v[182:185], v[210:213], v[98:101]
	v_mfma_f32_16x16x32_bf16 v[86:89], v[170:173], v[218:221], v[86:89]
	v_mfma_f32_16x16x32_bf16 v[82:85], v[182:185], v[218:221], v[82:85]
	v_mfma_f32_16x16x32_bf16 v[70:73], v[170:173], v[226:229], v[70:73]
	v_mfma_f32_16x16x32_bf16 v[66:69], v[182:185], v[226:229], v[66:69]
	v_mfma_f32_16x16x32_bf16 v[118:121], v[174:177], v[206:209], v[118:121]
	v_mfma_f32_16x16x32_bf16 v[114:117], v[198:201], v[206:209], v[114:117]
	v_mfma_f32_16x16x32_bf16 v[102:105], v[174:177], v[214:217], v[102:105]
	v_mfma_f32_16x16x32_bf16 v[98:101], v[198:201], v[214:217], v[98:101]
	v_mfma_f32_16x16x32_bf16 v[86:89], v[174:177], v[222:225], v[86:89]
	v_mfma_f32_16x16x32_bf16 v[82:85], v[198:201], v[222:225], v[82:85]
	v_mfma_f32_16x16x32_bf16 v[70:73], v[174:177], v[230:233], v[70:73]
	v_mfma_f32_16x16x32_bf16 v[66:69], v[198:201], v[230:233], v[66:69]
	s_setprio 0
	s_barrier
	s_add_i32 s26, s26, s84
	v_lshl_add_u64 v[234:235], s[22:23], 0, v[0:1]
	s_mov_b32 m0, s26
	ds_read_b128 v[202:205], v152 offset:16384
	ds_read_b128 v[206:209], v152 offset:17408
	ds_read_b128 v[210:213], v152 offset:18432
	ds_read_b128 v[214:217], v152 offset:19456
	ds_read_b128 v[218:221], v152 offset:20480
	ds_read_b128 v[222:225], v152 offset:21504
	ds_read_b128 v[226:229], v152 offset:22528
	ds_read_b128 v[230:233], v152 offset:23552
	global_load_lds_dwordx4 v[234:235], off
	s_add_i32 m0, s26, 0x2000
	v_lshl_add_u64 v[236:237], s[22:23], 0, v[134:135]
	s_add_u32 s22, s22, s52
	s_addc_u32 s23, s23, 0
	s_add_i32 s20, s20, s84
	global_load_lds_dwordx4 v[236:237], off
	v_lshl_add_u64 v[238:239], s[22:23], 0, v[0:1]
	s_mov_b32 m0, s20
	v_lshl_add_u64 v[240:241], s[22:23], 0, v[134:135]
	global_load_lds_dwordx4 v[238:239], off
	s_add_i32 m0, s20, 0x2000
	v_lshl_add_u64 v[242:243], s[74:75], 0, v[130:131]
	global_load_lds_dwordx4 v[240:241], off
	s_mov_b32 m0, s85
	v_lshl_add_u64 v[244:245], s[74:75], 0, v[132:133]
	global_load_lds_dwordx4 v[242:243], off
	s_mov_b32 m0, s86
	s_nop 0
	global_load_lds_dwordx4 v[244:245], off
	s_waitcnt vmcnt(8)
	s_waitcnt lgkmcnt(0)
	s_barrier
; #define PG8_STAGE(bufoff, gbase, voff) do { _Pragma("unroll") for (int _i = 0; _i < 2; ++_i) \
;         __builtin_amdgcn_global_load_lds((const unsigned*)((const char*)(gbase) + (voff)[_i]), (PG8_LAS unsigned*)(lds + (bufoff) + ldsw + _i * 8192), 16, 0, 0); } while (0)
; #define PG8_LDA(dst, b, h) do { _Pragma("unroll") for (int m = 0; m < 4; ++m) _Pragma("unroll") for (int k = 0; k < 2; ++k) dst[m][k] = *(const PG8_LAS bf16x8*)(lds + PG8_SA(b, h) + aoff + m * 2048 + k * 1024); } while (0)
; #define PG8_LDB(dst, b, h) do { _Pragma("unroll") for (int n = 0; n < 2; ++n) _Pragma("unroll") for (int k = 0; k < 2; ++k) dst[n][k] = *(const PG8_LAS bf16x8*)(lds + PG8_SB(b, h) + boff + n * 2048 + k * 1024); } while (0)
; #define PG8_MMA(ai, bj, At, Bt) do { __builtin_amdgcn_s_setprio(1); _Pragma("unroll") for (int m = 0; m < 4; ++m) _Pragma("unroll") for (int n = 0; n < 2; ++n) _Pragma("unroll") for (int k = 0; k < 2; ++k) \
;         acc[ai][bj][m][n] = __builtin_amdgcn_mfma_f32_16x16x32_bf16(Bt[n][k], At[m][k], acc[ai][bj][m][n], 0, 0, 0); __builtin_amdgcn_s_setprio(0); } while (0)
; #define PG8_WAIT_V(n) asm volatile("s_waitcnt vmcnt(" #n ")" ::: "memory")
; #define PG8_WAIT_L(n) asm volatile("s_waitcnt lgkmcnt(" #n ")" ::: "memory")
; #define PG8_BAR __builtin_amdgcn_s_barrier()
; #define PG8_SCHED __builtin_amdgcn_sched_barrier(0)
; template <class Epi, class Sched, bool ALIGN_EPI = false, bool SP2 = false>
; __device__ __forceinline__ void gemm_phase(PG8_LAS unsigned char* lds, const Gemm g, const Sched S, const Epi E) {
;     ...
;             PG8_WAIT_V(8); PG8_WAIT_L(0); PG8_BAR; PG8_MMA(1, 0, At, B0); PG8_MMA(1, 1, At, B1); PG8_BAR; PG8_SCHED;
;             PG8_LDB(B0, 1, 0); PG8_LDB(B1, 1, 1); PG8_SCHED; PG8_LDA(At, 1, 0); PG8_STAGE(PG8_SA(0, 1), a2 + hstep, voffA);
;             PG8_WAIT_V(8); PG8_WAIT_L(0); PG8_BAR; PG8_MMA(0, 0, At, B0); PG8_MMA(0, 1, At, B1); PG8_BAR; PG8_SCHED;
	s_setprio 1
	s_waitcnt lgkmcnt(0)
	v_mfma_f32_16x16x32_bf16 v[62:65], v[154:157], v[202:205], v[62:65]
	v_mfma_f32_16x16x32_bf16 v[58:61], v[162:165], v[202:205], v[58:61]
	v_mfma_f32_16x16x32_bf16 v[46:49], v[154:157], v[210:213], v[46:49]
	v_mfma_f32_16x16x32_bf16 v[42:45], v[162:165], v[210:213], v[42:45]
	v_mfma_f32_16x16x32_bf16 v[30:33], v[154:157], v[218:221], v[30:33]
	v_mfma_f32_16x16x32_bf16 v[26:29], v[162:165], v[218:221], v[26:29]
	v_mfma_f32_16x16x32_bf16 v[14:17], v[154:157], v[226:229], v[14:17]
	v_mfma_f32_16x16x32_bf16 v[10:13], v[162:165], v[226:229], v[10:13]
	v_mfma_f32_16x16x32_bf16 v[62:65], v[158:161], v[206:209], v[62:65]
	v_mfma_f32_16x16x32_bf16 v[58:61], v[166:169], v[206:209], v[58:61]
	v_mfma_f32_16x16x32_bf16 v[46:49], v[158:161], v[214:217], v[46:49]
	v_mfma_f32_16x16x32_bf16 v[42:45], v[166:169], v[214:217], v[42:45]
	v_mfma_f32_16x16x32_bf16 v[30:33], v[158:161], v[222:225], v[30:33]
	v_mfma_f32_16x16x32_bf16 v[26:29], v[166:169], v[222:225], v[26:29]
	v_mfma_f32_16x16x32_bf16 v[14:17], v[158:161], v[230:233], v[14:17]
	v_mfma_f32_16x16x32_bf16 v[10:13], v[166:169], v[230:233], v[10:13]
	s_setprio 0
	s_setprio 1
	v_mfma_f32_16x16x32_bf16 v[54:57], v[170:173], v[202:205], v[54:57]
	v_mfma_f32_16x16x32_bf16 v[50:53], v[182:185], v[202:205], v[50:53]
	v_mfma_f32_16x16x32_bf16 v[38:41], v[170:173], v[210:213], v[38:41]
	v_mfma_f32_16x16x32_bf16 v[34:37], v[182:185], v[210:213], v[34:37]
	v_mfma_f32_16x16x32_bf16 v[22:25], v[170:173], v[218:221], v[22:25]
	v_mfma_f32_16x16x32_bf16 v[18:21], v[182:185], v[218:221], v[18:21]
	v_mfma_f32_16x16x32_bf16 v[6:9], v[170:173], v[226:229], v[6:9]
	v_mfma_f32_16x16x32_bf16 v[2:5], v[182:185], v[226:229], v[2:5]
	v_mfma_f32_16x16x32_bf16 v[54:57], v[174:177], v[206:209], v[54:57]
	v_mfma_f32_16x16x32_bf16 v[50:53], v[198:201], v[206:209], v[50:53]
	v_mfma_f32_16x16x32_bf16 v[38:41], v[174:177], v[214:217], v[38:41]
	v_mfma_f32_16x16x32_bf16 v[34:37], v[198:201], v[214:217], v[34:37]
	v_mfma_f32_16x16x32_bf16 v[22:25], v[174:177], v[222:225], v[22:25]
	v_mfma_f32_16x16x32_bf16 v[18:21], v[198:201], v[222:225], v[18:21]
	v_mfma_f32_16x16x32_bf16 v[6:9], v[174:177], v[230:233], v[6:9]
	v_mfma_f32_16x16x32_bf16 v[2:5], v[198:201], v[230:233], v[2:5]
	s_setprio 0
	s_barrier
	s_add_i32 s20, 0, 0x18000
	v_add_u32_e32 v141, s20, v147
	s_add_i32 s26, 0, 0x1c000
	ds_read_b128 v[154:157], v141
	ds_read_b128 v[158:161], v141 offset:1024
	ds_read_b128 v[162:165], v141 offset:2048
	ds_read_b128 v[166:169], v141 offset:3072
	v_add_u32_e32 v141, s26, v147
	ds_read_b128 v[170:173], v141
	ds_read_b128 v[174:177], v141 offset:1024
	ds_read_b128 v[182:185], v141 offset:2048
	ds_read_b128 v[198:201], v141 offset:3072
	s_add_u32 s22, s74, s52
	s_addc_u32 s23, s75, 0
	s_mov_b32 m0, s87
	v_lshl_add_u64 v[246:247], s[22:23], 0, v[130:131]
	ds_read_b128 v[202:205], v152 offset:32768
	ds_read_b128 v[206:209], v152 offset:33792
	ds_read_b128 v[210:213], v152 offset:34816
	ds_read_b128 v[214:217], v152 offset:35840
	ds_read_b128 v[218:221], v152 offset:36864
	ds_read_b128 v[222:225], v152 offset:37888
	ds_read_b128 v[226:229], v152 offset:38912
	ds_read_b128 v[230:233], v152 offset:39936
	global_load_lds_dwordx4 v[246:247], off
	v_lshl_add_u64 v[246:247], s[22:23], 0, v[132:133]
	s_mov_b32 m0, s88
	s_nop 0
	global_load_lds_dwordx4 v[246:247], off
	s_waitcnt vmcnt(8)
	s_waitcnt lgkmcnt(0)
	s_barrier
	s_setprio 1
	s_waitcnt lgkmcnt(0)
	v_mfma_f32_16x16x32_bf16 v[126:129], v[154:157], v[202:205], v[126:129]
	v_mfma_f32_16x16x32_bf16 v[122:125], v[162:165], v[202:205], v[122:125]
	v_mfma_f32_16x16x32_bf16 v[110:113], v[154:157], v[210:213], v[110:113]
	v_mfma_f32_16x16x32_bf16 v[106:109], v[162:165], v[210:213], v[106:109]
	v_mfma_f32_16x16x32_bf16 v[94:97], v[154:157], v[218:221], v[94:97]
	v_mfma_f32_16x16x32_bf16 v[90:93], v[162:165], v[218:221], v[90:93]
	v_mfma_f32_16x16x32_bf16 v[78:81], v[154:157], v[226:229], v[78:81]
	v_mfma_f32_16x16x32_bf16 v[74:77], v[162:165], v[226:229], v[74:77]
	v_mfma_f32_16x16x32_bf16 v[126:129], v[158:161], v[206:209], v[126:129]
	v_mfma_f32_16x16x32_bf16 v[122:125], v[166:169], v[206:209], v[122:125]
	v_mfma_f32_16x16x32_bf16 v[110:113], v[158:161], v[214:217], v[110:113]
	v_mfma_f32_16x16x32_bf16 v[106:109], v[166:169], v[214:217], v[106:109]
	v_mfma_f32_16x16x32_bf16 v[94:97], v[158:161], v[222:225], v[94:97]
	v_mfma_f32_16x16x32_bf16 v[90:93], v[166:169], v[222:225], v[90:93]
	v_mfma_f32_16x16x32_bf16 v[78:81], v[158:161], v[230:233], v[78:81]
	v_mfma_f32_16x16x32_bf16 v[74:77], v[166:169], v[230:233], v[74:77]
	s_setprio 0
	s_setprio 1
	v_mfma_f32_16x16x32_bf16 v[118:121], v[170:173], v[202:205], v[118:121]
	v_mfma_f32_16x16x32_bf16 v[114:117], v[182:185], v[202:205], v[114:117]
	v_mfma_f32_16x16x32_bf16 v[102:105], v[170:173], v[210:213], v[102:105]
	v_mfma_f32_16x16x32_bf16 v[98:101], v[182:185], v[210:213], v[98:101]
	v_mfma_f32_16x16x32_bf16 v[86:89], v[170:173], v[218:221], v[86:89]
	v_mfma_f32_16x16x32_bf16 v[82:85], v[182:185], v[218:221], v[82:85]
	v_mfma_f32_16x16x32_bf16 v[70:73], v[170:173], v[226:229], v[70:73]
	v_mfma_f32_16x16x32_bf16 v[66:69], v[182:185], v[226:229], v[66:69]
	v_mfma_f32_16x16x32_bf16 v[118:121], v[174:177], v[206:209], v[118:121]
	v_mfma_f32_16x16x32_bf16 v[114:117], v[198:201], v[206:209], v[114:117]
	v_mfma_f32_16x16x32_bf16 v[102:105], v[174:177], v[214:217], v[102:105]
	v_mfma_f32_16x16x32_bf16 v[98:101], v[198:201], v[214:217], v[98:101]
	v_mfma_f32_16x16x32_bf16 v[86:89], v[174:177], v[222:225], v[86:89]
	v_mfma_f32_16x16x32_bf16 v[82:85], v[198:201], v[222:225], v[82:85]
	v_mfma_f32_16x16x32_bf16 v[70:73], v[174:177], v[230:233], v[70:73]
	v_mfma_f32_16x16x32_bf16 v[66:69], v[198:201], v[230:233], v[66:69]
	s_setprio 0
	s_barrier
; #define PG8_STAGE(bufoff, gbase, voff) do { _Pragma("unroll") for (int _i = 0; _i < 2; ++_i) \
;         __builtin_amdgcn_global_load_lds((const unsigned*)((const char*)(gbase) + (voff)[_i]), (PG8_LAS unsigned*)(lds + (bufoff) + ldsw + _i * 8192), 16, 0, 0); } while (0)
; #define PG8_LDA(dst, b, h) do { _Pragma("unroll") for (int m = 0; m < 4; ++m) _Pragma("unroll") for (int k = 0; k < 2; ++k) dst[m][k] = *(const PG8_LAS bf16x8*)(lds + PG8_SA(b, h) + aoff + m * 2048 + k * 1024); } while (0)
; #define PG8_MMA(ai, bj, At, Bt) do { __builtin_amdgcn_s_setprio(1); _Pragma("unroll") for (int m = 0; m < 4; ++m) _Pragma("unroll") for (int n = 0; n < 2; ++n) _Pragma("unroll") for (int k = 0; k < 2; ++k) \
;         acc[ai][bj][m][n] = __builtin_amdgcn_mfma_f32_16x16x32_bf16(Bt[n][k], At[m][k], acc[ai][bj][m][n], 0, 0, 0); __builtin_amdgcn_s_setprio(0); } while (0)
; #define PG8_WAIT_V(n) asm volatile("s_waitcnt vmcnt(" #n ")" ::: "memory")
; #define PG8_WAIT_L(n) asm volatile("s_waitcnt lgkmcnt(" #n ")" ::: "memory")
; #define PG8_BAR __builtin_amdgcn_s_barrier()
; #define PG8_SCHED __builtin_amdgcn_sched_barrier(0)
; template <class Epi, class Sched, bool ALIGN_EPI = false, bool SP2 = false>
; __device__ __forceinline__ void gemm_phase(PG8_LAS unsigned char* lds, const Gemm g, const Sched S, const Epi E) {
;     ...
;         for (int t = 0; t < nt; t += 2) {
;             const bool last = (t == nt - 2);
;             const char* a1 = cA + (size_t)(t + 1) * kstep;
;             const char* a2 = last ? nA : cA + (size_t)(t + 2) * kstep; const char* b2 = last ? nB : cB + (size_t)(t + 2) * kstep;
;     ...
;             PG8_LDA(At, 1, 1); PG8_STAGE(PG8_SB(1, 0), b3, voffB); PG8_STAGE(PG8_SB(1, 1), b3 + hstep, voffB); PG8_STAGE(PG8_SA(1, 0), a3, voffA);
;             PG8_WAIT_V(8); PG8_WAIT_L(0); PG8_BAR; PG8_MMA(1, 0, At, B0); PG8_MMA(1, 1, At, B1); PG8_BAR; PG8_SCHED;
	s_add_i32 s20, s20, s84
	v_lshl_add_u64 v[234:235], v[234:235], 0, s[12:13]
	s_mov_b32 m0, s20
	ds_read_b128 v[202:205], v152 offset:49152
	ds_read_b128 v[206:209], v152 offset:50176
	ds_read_b128 v[210:213], v152 offset:51200
	ds_read_b128 v[214:217], v152 offset:52224
	ds_read_b128 v[218:221], v152 offset:53248
	ds_read_b128 v[222:225], v152 offset:54272
	ds_read_b128 v[226:229], v152 offset:55296
	ds_read_b128 v[230:233], v152 offset:56320
	global_load_lds_dwordx4 v[234:235], off
	v_lshl_add_u64 v[234:235], v[236:237], 0, s[12:13]
	s_add_i32 m0, s20, 0x2000
	s_add_i32 s20, s26, s84
	global_load_lds_dwordx4 v[234:235], off
	v_lshl_add_u64 v[234:235], v[238:239], 0, s[12:13]
	s_mov_b32 m0, s20
	s_nop 0
	global_load_lds_dwordx4 v[234:235], off
	v_lshl_add_u64 v[234:235], v[240:241], 0, s[12:13]
	s_add_i32 m0, s20, 0x2000
	s_nop 0
	global_load_lds_dwordx4 v[234:235], off
	v_lshl_add_u64 v[234:235], v[242:243], 0, s[12:13]
	s_mov_b32 m0, s3
	s_nop 0
	global_load_lds_dwordx4 v[234:235], off
	v_lshl_add_u64 v[234:235], v[244:245], 0, s[12:13]
	s_mov_b32 m0, s24
	s_nop 0
	global_load_lds_dwordx4 v[234:235], off
	s_waitcnt vmcnt(8)
	s_waitcnt lgkmcnt(0)
	s_barrier
	s_setprio 1
	s_waitcnt lgkmcnt(0)
	v_mfma_f32_16x16x32_bf16 v[62:65], v[154:157], v[202:205], v[62:65]
	v_mfma_f32_16x16x32_bf16 v[58:61], v[162:165], v[202:205], v[58:61]
	v_mfma_f32_16x16x32_bf16 v[46:49], v[154:157], v[210:213], v[46:49]
	v_mfma_f32_16x16x32_bf16 v[42:45], v[162:165], v[210:213], v[42:45]
	v_mfma_f32_16x16x32_bf16 v[30:33], v[154:157], v[218:221], v[30:33]
	v_mfma_f32_16x16x32_bf16 v[26:29], v[162:165], v[218:221], v[26:29]
	v_mfma_f32_16x16x32_bf16 v[14:17], v[154:157], v[226:229], v[14:17]
	v_mfma_f32_16x16x32_bf16 v[10:13], v[162:165], v[226:229], v[10:13]
	v_mfma_f32_16x16x32_bf16 v[62:65], v[158:161], v[206:209], v[62:65]
	v_mfma_f32_16x16x32_bf16 v[58:61], v[166:169], v[206:209], v[58:61]
	v_mfma_f32_16x16x32_bf16 v[46:49], v[158:161], v[214:217], v[46:49]
	v_mfma_f32_16x16x32_bf16 v[42:45], v[166:169], v[214:217], v[42:45]
	v_mfma_f32_16x16x32_bf16 v[30:33], v[158:161], v[222:225], v[30:33]
	v_mfma_f32_16x16x32_bf16 v[26:29], v[166:169], v[222:225], v[26:29]
	v_mfma_f32_16x16x32_bf16 v[14:17], v[158:161], v[230:233], v[14:17]
	v_mfma_f32_16x16x32_bf16 v[10:13], v[166:169], v[230:233], v[10:13]
	s_setprio 0
	s_setprio 1
	v_mfma_f32_16x16x32_bf16 v[54:57], v[170:173], v[202:205], v[54:57]
	v_mfma_f32_16x16x32_bf16 v[50:53], v[182:185], v[202:205], v[50:53]
	v_mfma_f32_16x16x32_bf16 v[38:41], v[170:173], v[210:213], v[38:41]
	v_mfma_f32_16x16x32_bf16 v[34:37], v[182:185], v[210:213], v[34:37]
	v_mfma_f32_16x16x32_bf16 v[22:25], v[170:173], v[218:221], v[22:25]
	v_mfma_f32_16x16x32_bf16 v[18:21], v[182:185], v[218:221], v[18:21]
	v_mfma_f32_16x16x32_bf16 v[6:9], v[170:173], v[226:229], v[6:9]
	v_mfma_f32_16x16x32_bf16 v[2:5], v[182:185], v[226:229], v[2:5]
	v_mfma_f32_16x16x32_bf16 v[54:57], v[174:177], v[206:209], v[54:57]
	v_mfma_f32_16x16x32_bf16 v[50:53], v[198:201], v[206:209], v[50:53]
	v_mfma_f32_16x16x32_bf16 v[38:41], v[174:177], v[214:217], v[38:41]
	v_mfma_f32_16x16x32_bf16 v[34:37], v[198:201], v[214:217], v[34:37]
	v_mfma_f32_16x16x32_bf16 v[22:25], v[174:177], v[222:225], v[22:25]
	v_mfma_f32_16x16x32_bf16 v[18:21], v[198:201], v[222:225], v[18:21]
	v_mfma_f32_16x16x32_bf16 v[6:9], v[174:177], v[230:233], v[6:9]
	v_mfma_f32_16x16x32_bf16 v[2:5], v[198:201], v[230:233], v[2:5]
	s_setprio 0
	s_add_u32 s30, s30, 0x100
	s_addc_u32 s31, s31, 0
	s_add_u32 s14, s14, 0x100
	s_addc_u32 s15, s15, 0
	s_cmp_ge_u32 s21, s80
	s_mov_b32 s20, s21
	s_barrier
	s_cbranch_scc0 .LBB0_224
	s_and_b64 vcc, exec, s[16:17]
	s_cbranch_vccz .LBB0_227
	s_barrier

; #define PG8_STAGE(bufoff, gbase, voff) do { _Pragma("unroll") for (int _i = 0; _i < 2; ++_i) \
;         __builtin_amdgcn_global_load_lds((const unsigned*)((const char*)(gbase) + (voff)[_i]), (PG8_LAS unsigned*)(lds + (bufoff) + ldsw + _i * 8192), 16, 0, 0); } while (0)
; #define PG8_LDA(dst, b, h) do { _Pragma("unroll") for (int m = 0; m < 4; ++m) _Pragma("unroll") for (int k = 0; k < 2; ++k) dst[m][k] = *(const PG8_LAS bf16x8*)(lds + PG8_SA(b, h) + aoff + m * 2048 + k * 1024); } while (0)
; #define PG8_LDB(dst, b, h) do { _Pragma("unroll") for (int n = 0; n < 2; ++n) _Pragma("unroll") for (int k = 0; k < 2; ++k) dst[n][k] = *(const PG8_LAS bf16x8*)(lds + PG8_SB(b, h) + boff + n * 2048 + k * 1024); } while (0)
; #define PG8_MMA(ai, bj, At, Bt) do { __builtin_amdgcn_s_setprio(1); _Pragma("unroll") for (int m = 0; m < 4; ++m) _Pragma("unroll") for (int n = 0; n < 2; ++n) _Pragma("unroll") for (int k = 0; k < 2; ++k) \
;         acc[ai][bj][m][n] = __builtin_amdgcn_mfma_f32_16x16x32_bf16(Bt[n][k], At[m][k], acc[ai][bj][m][n], 0, 0, 0); __builtin_amdgcn_s_setprio(0); } while (0)
; #define PG8_WAIT_V(n) asm volatile("s_waitcnt vmcnt(" #n ")" ::: "memory")
; #define PG8_WAIT_L(n) asm volatile("s_waitcnt lgkmcnt(" #n ")" ::: "memory")
; #define PG8_BAR __builtin_amdgcn_s_barrier()
; #define PG8_SCHED __builtin_amdgcn_sched_barrier(0)
; template <class Epi, class Sched, bool ALIGN_EPI = false, bool SP2 = false>
; __device__ __forceinline__ void gemm_phase(PG8_LAS unsigned char* lds, const Gemm g, const Sched S, const Epi E) {
;     ...
;             const bool last = (t == nt - 2);
;             const char* a1 = cA + (size_t)(t + 1) * kstep;
;             const char* a2 = last ? nA : cA + (size_t)(t + 2) * kstep; const char* b2 = last ? nB : cB + (size_t)(t + 2) * kstep;
;             const char* a3 = a2 + kstep; const char* b3 = b2 + kstep;
;             if (last && has_next) S.a_ready(nxt);
;             if constexpr (SP2) {
;             PG8_LDB(B0, 0, 0); PG8_LDB(B1, 0, 1); PG8_SCHED; PG8_LDA(At, 0, 0); PG8_STAGE(PG8_SA(1, 1), a1 + hstep, voffA);
;             PG8_WAIT_V(8); PG8_WAIT_L(0); PG8_BAR; PG8_MMA(0, 0, At, B0); PG8_MMA(0, 1, At, B1); PG8_BAR; PG8_SCHED;
;             PG8_LDA(At, 0, 1); PG8_STAGE(PG8_SB(0, 0), b2, voffB); PG8_STAGE(PG8_SB(0, 1), b2 + hstep, voffB); PG8_STAGE(PG8_SA(0, 0), a2, voffA);
.LBB0_416:
	s_add_i32 s3, s14, 2
	s_add_u32 s15, s68, s16
	s_addc_u32 s18, s69, s17
	s_add_u32 s20, s66, s16
	s_addc_u32 s21, s67, s17
	s_add_i32 s22, 0, 0x10000
	s_cmp_eq_u32 s89, s14
	s_cselect_b32 s19, s1, s18
	s_cselect_b32 s18, s0, s15
	s_cselect_b32 s15, s71, s21
	s_cselect_b32 s14, s70, s20
	s_add_i32 s20, 0, 0x14000
	v_add_u32_e32 v158, s22, v168
	v_add_u32_e32 v171, s20, v168
	ds_read_b128 v[134:137], v158
	ds_read_b128 v[138:141], v158 offset:1024
	ds_read_b128 v[142:145], v158 offset:2048
	ds_read_b128 v[158:161], v158 offset:3072
	ds_read_b128 v[162:165], v171
	ds_read_b128 v[172:175], v171 offset:1024
	ds_read_b128 v[182:185], v171 offset:2048
	ds_read_b128 v[198:201], v171 offset:3072
	v_lshl_add_u64 v[176:177], s[68:69], 0, v[132:133]
	s_add_i32 m0, s80, 0xc000
	ds_read_b128 v[202:205], v170
	ds_read_b128 v[206:209], v170 offset:1024
	ds_read_b128 v[210:213], v170 offset:2048
	ds_read_b128 v[214:217], v170 offset:3072
	ds_read_b128 v[218:221], v170 offset:4096
	ds_read_b128 v[222:225], v170 offset:5120
	ds_read_b128 v[226:229], v170 offset:6144
	ds_read_b128 v[230:233], v170 offset:7168
	global_load_lds_dwordx4 v[176:177], off
	v_lshl_add_u64 v[176:177], s[68:69], 0, v[130:131]
	s_add_i32 m0, s80, 0xe000
	s_nop 0
	global_load_lds_dwordx4 v[176:177], off
	s_waitcnt vmcnt(8)
	s_waitcnt lgkmcnt(0)
	s_barrier
	s_setprio 1
	s_waitcnt lgkmcnt(0)
	v_mfma_f32_16x16x32_bf16 v[58:61], v[134:137], v[202:205], v[58:61]
	v_mfma_f32_16x16x32_bf16 v[50:53], v[142:145], v[202:205], v[50:53]
	v_mfma_f32_16x16x32_bf16 v[14:17], v[134:137], v[210:213], v[14:17]
	v_mfma_f32_16x16x32_bf16 v[10:13], v[142:145], v[210:213], v[10:13]
	v_mfma_f32_16x16x32_bf16 v[30:33], v[134:137], v[218:221], v[30:33]
	v_mfma_f32_16x16x32_bf16 v[26:29], v[142:145], v[218:221], v[26:29]
	v_mfma_f32_16x16x32_bf16 v[46:49], v[134:137], v[226:229], v[46:49]
	v_mfma_f32_16x16x32_bf16 v[42:45], v[142:145], v[226:229], v[42:45]
	v_mfma_f32_16x16x32_bf16 v[58:61], v[138:141], v[206:209], v[58:61]
	v_mfma_f32_16x16x32_bf16 v[50:53], v[158:161], v[206:209], v[50:53]
	v_mfma_f32_16x16x32_bf16 v[14:17], v[138:141], v[214:217], v[14:17]
	v_mfma_f32_16x16x32_bf16 v[10:13], v[158:161], v[214:217], v[10:13]
	v_mfma_f32_16x16x32_bf16 v[30:33], v[138:141], v[222:225], v[30:33]
	v_mfma_f32_16x16x32_bf16 v[26:29], v[158:161], v[222:225], v[26:29]
	v_mfma_f32_16x16x32_bf16 v[46:49], v[138:141], v[230:233], v[46:49]
	v_mfma_f32_16x16x32_bf16 v[42:45], v[158:161], v[230:233], v[42:45]
	s_setprio 0
	s_setprio 1
	v_mfma_f32_16x16x32_bf16 v[6:9], v[162:165], v[202:205], v[6:9]
	v_mfma_f32_16x16x32_bf16 v[2:5], v[182:185], v[202:205], v[2:5]
	v_mfma_f32_16x16x32_bf16 v[22:25], v[162:165], v[210:213], v[22:25]
	v_mfma_f32_16x16x32_bf16 v[18:21], v[182:185], v[210:213], v[18:21]
	v_mfma_f32_16x16x32_bf16 v[38:41], v[162:165], v[218:221], v[38:41]
	v_mfma_f32_16x16x32_bf16 v[34:37], v[182:185], v[218:221], v[34:37]
	v_mfma_f32_16x16x32_bf16 v[62:65], v[162:165], v[226:229], v[62:65]
	v_mfma_f32_16x16x32_bf16 v[54:57], v[182:185], v[226:229], v[54:57]
	v_mfma_f32_16x16x32_bf16 v[6:9], v[172:175], v[206:209], v[6:9]
	v_mfma_f32_16x16x32_bf16 v[2:5], v[198:201], v[206:209], v[2:5]
	v_mfma_f32_16x16x32_bf16 v[22:25], v[172:175], v[214:217], v[22:25]
	v_mfma_f32_16x16x32_bf16 v[18:21], v[198:201], v[214:217], v[18:21]
	v_mfma_f32_16x16x32_bf16 v[38:41], v[172:175], v[222:225], v[38:41]
	v_mfma_f32_16x16x32_bf16 v[34:37], v[198:201], v[222:225], v[34:37]
	v_mfma_f32_16x16x32_bf16 v[62:65], v[172:175], v[230:233], v[62:65]
	v_mfma_f32_16x16x32_bf16 v[54:57], v[198:201], v[230:233], v[54:57]
	s_setprio 0
	s_barrier
	s_add_i32 s21, s22, s79
	v_lshl_add_u64 v[176:177], s[14:15], 0, v[148:149]
	s_mov_b32 m0, s21
	ds_read_b128 v[202:205], v170 offset:16384
	ds_read_b128 v[206:209], v170 offset:17408
	ds_read_b128 v[210:213], v170 offset:18432
	ds_read_b128 v[214:217], v170 offset:19456
	ds_read_b128 v[218:221], v170 offset:20480
	ds_read_b128 v[222:225], v170 offset:21504
	ds_read_b128 v[226:229], v170 offset:22528
	ds_read_b128 v[230:233], v170 offset:23552
	global_load_lds_dwordx4 v[176:177], off
	s_add_i32 m0, s21, 0x2000
	v_lshl_add_u64 v[234:235], s[14:15], 0, v[152:153]
	s_add_u32 s14, s14, s28
	s_addc_u32 s15, s15, 0
	s_add_i32 s20, s20, s79
	global_load_lds_dwordx4 v[234:235], off
	v_lshl_add_u64 v[236:237], s[14:15], 0, v[148:149]
	s_mov_b32 m0, s20
	v_lshl_add_u64 v[238:239], s[14:15], 0, v[152:153]
	global_load_lds_dwordx4 v[236:237], off
	s_add_i32 m0, s20, 0x2000
	v_lshl_add_u64 v[240:241], s[18:19], 0, v[146:147]
	global_load_lds_dwordx4 v[238:239], off
	s_mov_b32 m0, s80
	v_lshl_add_u64 v[242:243], s[18:19], 0, v[150:151]
	global_load_lds_dwordx4 v[240:241], off
	s_mov_b32 m0, s81
	s_nop 0
	global_load_lds_dwordx4 v[242:243], off
	s_waitcnt vmcnt(8)
	s_waitcnt lgkmcnt(0)
	s_barrier
; #define PG8_STAGE(bufoff, gbase, voff) do { _Pragma("unroll") for (int _i = 0; _i < 2; ++_i) \
;         __builtin_amdgcn_global_load_lds((const unsigned*)((const char*)(gbase) + (voff)[_i]), (PG8_LAS unsigned*)(lds + (bufoff) + ldsw + _i * 8192), 16, 0, 0); } while (0)
; #define PG8_LDA(dst, b, h) do { _Pragma("unroll") for (int m = 0; m < 4; ++m) _Pragma("unroll") for (int k = 0; k < 2; ++k) dst[m][k] = *(const PG8_LAS bf16x8*)(lds + PG8_SA(b, h) + aoff + m * 2048 + k * 1024); } while (0)
; #define PG8_LDB(dst, b, h) do { _Pragma("unroll") for (int n = 0; n < 2; ++n) _Pragma("unroll") for (int k = 0; k < 2; ++k) dst[n][k] = *(const PG8_LAS bf16x8*)(lds + PG8_SB(b, h) + boff + n * 2048 + k * 1024); } while (0)
; #define PG8_MMA(ai, bj, At, Bt) do { __builtin_amdgcn_s_setprio(1); _Pragma("unroll") for (int m = 0; m < 4; ++m) _Pragma("unroll") for (int n = 0; n < 2; ++n) _Pragma("unroll") for (int k = 0; k < 2; ++k) \
;         acc[ai][bj][m][n] = __builtin_amdgcn_mfma_f32_16x16x32_bf16(Bt[n][k], At[m][k], acc[ai][bj][m][n], 0, 0, 0); __builtin_amdgcn_s_setprio(0); } while (0)
; #define PG8_WAIT_V(n) asm volatile("s_waitcnt vmcnt(" #n ")" ::: "memory")
; #define PG8_WAIT_L(n) asm volatile("s_waitcnt lgkmcnt(" #n ")" ::: "memory")
; #define PG8_BAR __builtin_amdgcn_s_barrier()
; #define PG8_SCHED __builtin_amdgcn_sched_barrier(0)
; template <class Epi, class Sched, bool ALIGN_EPI = false, bool SP2 = false>
; __device__ __forceinline__ void gemm_phase(PG8_LAS unsigned char* lds, const Gemm g, const Sched S, const Epi E) {
;     ...
;             PG8_WAIT_V(8); PG8_WAIT_L(0); PG8_BAR; PG8_MMA(1, 0, At, B0); PG8_MMA(1, 1, At, B1); PG8_BAR; PG8_SCHED;
;             PG8_LDB(B0, 1, 0); PG8_LDB(B1, 1, 1); PG8_SCHED; PG8_LDA(At, 1, 0); PG8_STAGE(PG8_SA(0, 1), a2 + hstep, voffA);
;             PG8_WAIT_V(8); PG8_WAIT_L(0); PG8_BAR; PG8_MMA(0, 0, At, B0); PG8_MMA(0, 1, At, B1); PG8_BAR; PG8_SCHED;
	s_setprio 1
	s_waitcnt lgkmcnt(0)
	v_mfma_f32_16x16x32_bf16 v[70:73], v[134:137], v[202:205], v[70:73]
	v_mfma_f32_16x16x32_bf16 v[66:69], v[142:145], v[202:205], v[66:69]
	v_mfma_f32_16x16x32_bf16 v[86:89], v[134:137], v[210:213], v[86:89]
	v_mfma_f32_16x16x32_bf16 v[82:85], v[142:145], v[210:213], v[82:85]
	v_mfma_f32_16x16x32_bf16 v[102:105], v[134:137], v[218:221], v[102:105]
	v_mfma_f32_16x16x32_bf16 v[98:101], v[142:145], v[218:221], v[98:101]
	v_mfma_f32_16x16x32_bf16 v[118:121], v[134:137], v[226:229], v[118:121]
	v_mfma_f32_16x16x32_bf16 v[114:117], v[142:145], v[226:229], v[114:117]
	v_mfma_f32_16x16x32_bf16 v[70:73], v[138:141], v[206:209], v[70:73]
	v_mfma_f32_16x16x32_bf16 v[66:69], v[158:161], v[206:209], v[66:69]
	v_mfma_f32_16x16x32_bf16 v[86:89], v[138:141], v[214:217], v[86:89]
	v_mfma_f32_16x16x32_bf16 v[82:85], v[158:161], v[214:217], v[82:85]
	v_mfma_f32_16x16x32_bf16 v[102:105], v[138:141], v[222:225], v[102:105]
	v_mfma_f32_16x16x32_bf16 v[98:101], v[158:161], v[222:225], v[98:101]
	v_mfma_f32_16x16x32_bf16 v[118:121], v[138:141], v[230:233], v[118:121]
	v_mfma_f32_16x16x32_bf16 v[114:117], v[158:161], v[230:233], v[114:117]
	s_setprio 0
	s_setprio 1
	v_mfma_f32_16x16x32_bf16 v[78:81], v[162:165], v[202:205], v[78:81]
	v_mfma_f32_16x16x32_bf16 v[74:77], v[182:185], v[202:205], v[74:77]
	v_mfma_f32_16x16x32_bf16 v[94:97], v[162:165], v[210:213], v[94:97]
	v_mfma_f32_16x16x32_bf16 v[90:93], v[182:185], v[210:213], v[90:93]
	v_mfma_f32_16x16x32_bf16 v[110:113], v[162:165], v[218:221], v[110:113]
	v_mfma_f32_16x16x32_bf16 v[106:109], v[182:185], v[218:221], v[106:109]
	v_mfma_f32_16x16x32_bf16 v[126:129], v[162:165], v[226:229], v[126:129]
	v_mfma_f32_16x16x32_bf16 v[122:125], v[182:185], v[226:229], v[122:125]
	v_mfma_f32_16x16x32_bf16 v[78:81], v[172:175], v[206:209], v[78:81]
	v_mfma_f32_16x16x32_bf16 v[74:77], v[198:201], v[206:209], v[74:77]
	v_mfma_f32_16x16x32_bf16 v[94:97], v[172:175], v[214:217], v[94:97]
	v_mfma_f32_16x16x32_bf16 v[90:93], v[198:201], v[214:217], v[90:93]
	v_mfma_f32_16x16x32_bf16 v[110:113], v[172:175], v[222:225], v[110:113]
	v_mfma_f32_16x16x32_bf16 v[106:109], v[198:201], v[222:225], v[106:109]
	v_mfma_f32_16x16x32_bf16 v[126:129], v[172:175], v[230:233], v[126:129]
	v_mfma_f32_16x16x32_bf16 v[122:125], v[198:201], v[230:233], v[122:125]
	s_setprio 0
	s_barrier
	s_add_i32 s20, 0, 0x18000
	s_add_i32 s21, 0, 0x1c000
	v_add_u32_e32 v158, s20, v168
	v_add_u32_e32 v171, s21, v168
	ds_read_b128 v[134:137], v158
	ds_read_b128 v[138:141], v158 offset:1024
	ds_read_b128 v[142:145], v158 offset:2048
	ds_read_b128 v[158:161], v158 offset:3072
	ds_read_b128 v[162:165], v171
	ds_read_b128 v[172:175], v171 offset:1024
	ds_read_b128 v[182:185], v171 offset:2048
	ds_read_b128 v[198:201], v171 offset:3072
	s_add_u32 s14, s18, s28
	s_addc_u32 s15, s19, 0
	s_mov_b32 m0, s82
	v_lshl_add_u64 v[244:245], s[14:15], 0, v[146:147]
	ds_read_b128 v[202:205], v170 offset:32768
	ds_read_b128 v[206:209], v170 offset:33792
	ds_read_b128 v[210:213], v170 offset:34816
	ds_read_b128 v[214:217], v170 offset:35840
	ds_read_b128 v[218:221], v170 offset:36864
	ds_read_b128 v[222:225], v170 offset:37888
	ds_read_b128 v[226:229], v170 offset:38912
	ds_read_b128 v[230:233], v170 offset:39936
	global_load_lds_dwordx4 v[244:245], off
	v_lshl_add_u64 v[244:245], s[14:15], 0, v[150:151]
	s_mov_b32 m0, s83
	s_nop 0
	global_load_lds_dwordx4 v[244:245], off
	s_waitcnt vmcnt(8)
	s_waitcnt lgkmcnt(0)
	s_barrier
	s_setprio 1
	s_waitcnt lgkmcnt(0)
	v_mfma_f32_16x16x32_bf16 v[58:61], v[134:137], v[202:205], v[58:61]
	v_mfma_f32_16x16x32_bf16 v[50:53], v[142:145], v[202:205], v[50:53]
	v_mfma_f32_16x16x32_bf16 v[14:17], v[134:137], v[210:213], v[14:17]
	v_mfma_f32_16x16x32_bf16 v[10:13], v[142:145], v[210:213], v[10:13]
	v_mfma_f32_16x16x32_bf16 v[30:33], v[134:137], v[218:221], v[30:33]
	v_mfma_f32_16x16x32_bf16 v[26:29], v[142:145], v[218:221], v[26:29]
	v_mfma_f32_16x16x32_bf16 v[46:49], v[134:137], v[226:229], v[46:49]
	v_mfma_f32_16x16x32_bf16 v[42:45], v[142:145], v[226:229], v[42:45]
	v_mfma_f32_16x16x32_bf16 v[58:61], v[138:141], v[206:209], v[58:61]
	v_mfma_f32_16x16x32_bf16 v[50:53], v[158:161], v[206:209], v[50:53]
	v_mfma_f32_16x16x32_bf16 v[14:17], v[138:141], v[214:217], v[14:17]
	v_mfma_f32_16x16x32_bf16 v[10:13], v[158:161], v[214:217], v[10:13]
	v_mfma_f32_16x16x32_bf16 v[30:33], v[138:141], v[222:225], v[30:33]
	v_mfma_f32_16x16x32_bf16 v[26:29], v[158:161], v[222:225], v[26:29]
	v_mfma_f32_16x16x32_bf16 v[46:49], v[138:141], v[230:233], v[46:49]
	v_mfma_f32_16x16x32_bf16 v[42:45], v[158:161], v[230:233], v[42:45]
	s_setprio 0
	s_setprio 1
	v_mfma_f32_16x16x32_bf16 v[6:9], v[162:165], v[202:205], v[6:9]
	v_mfma_f32_16x16x32_bf16 v[2:5], v[182:185], v[202:205], v[2:5]
	v_mfma_f32_16x16x32_bf16 v[22:25], v[162:165], v[210:213], v[22:25]
	v_mfma_f32_16x16x32_bf16 v[18:21], v[182:185], v[210:213], v[18:21]
	v_mfma_f32_16x16x32_bf16 v[38:41], v[162:165], v[218:221], v[38:41]
	v_mfma_f32_16x16x32_bf16 v[34:37], v[182:185], v[218:221], v[34:37]
	v_mfma_f32_16x16x32_bf16 v[62:65], v[162:165], v[226:229], v[62:65]
	v_mfma_f32_16x16x32_bf16 v[54:57], v[182:185], v[226:229], v[54:57]
	v_mfma_f32_16x16x32_bf16 v[6:9], v[172:175], v[206:209], v[6:9]
	v_mfma_f32_16x16x32_bf16 v[2:5], v[198:201], v[206:209], v[2:5]
	v_mfma_f32_16x16x32_bf16 v[22:25], v[172:175], v[214:217], v[22:25]
	v_mfma_f32_16x16x32_bf16 v[18:21], v[198:201], v[214:217], v[18:21]
	v_mfma_f32_16x16x32_bf16 v[38:41], v[172:175], v[222:225], v[38:41]
	v_mfma_f32_16x16x32_bf16 v[34:37], v[198:201], v[222:225], v[34:37]
	v_mfma_f32_16x16x32_bf16 v[62:65], v[172:175], v[230:233], v[62:65]
	v_mfma_f32_16x16x32_bf16 v[54:57], v[198:201], v[230:233], v[54:57]
	s_setprio 0
	s_barrier
; #define PG8_STAGE(bufoff, gbase, voff) do { _Pragma("unroll") for (int _i = 0; _i < 2; ++_i) \
;         __builtin_amdgcn_global_load_lds((const unsigned*)((const char*)(gbase) + (voff)[_i]), (PG8_LAS unsigned*)(lds + (bufoff) + ldsw + _i * 8192), 16, 0, 0); } while (0)
; #define PG8_LDA(dst, b, h) do { _Pragma("unroll") for (int m = 0; m < 4; ++m) _Pragma("unroll") for (int k = 0; k < 2; ++k) dst[m][k] = *(const PG8_LAS bf16x8*)(lds + PG8_SA(b, h) + aoff + m * 2048 + k * 1024); } while (0)
; #define PG8_MMA(ai, bj, At, Bt) do { __builtin_amdgcn_s_setprio(1); _Pragma("unroll") for (int m = 0; m < 4; ++m) _Pragma("unroll") for (int n = 0; n < 2; ++n) _Pragma("unroll") for (int k = 0; k < 2; ++k) \
;         acc[ai][bj][m][n] = __builtin_amdgcn_mfma_f32_16x16x32_bf16(Bt[n][k], At[m][k], acc[ai][bj][m][n], 0, 0, 0); __builtin_amdgcn_s_setprio(0); } while (0)
; #define PG8_WAIT_V(n) asm volatile("s_waitcnt vmcnt(" #n ")" ::: "memory")
; #define PG8_WAIT_L(n) asm volatile("s_waitcnt lgkmcnt(" #n ")" ::: "memory")
; #define PG8_BAR __builtin_amdgcn_s_barrier()
; #define PG8_SCHED __builtin_amdgcn_sched_barrier(0)
; template <class Epi, class Sched, bool ALIGN_EPI = false, bool SP2 = false>
; __device__ __forceinline__ void gemm_phase(PG8_LAS unsigned char* lds, const Gemm g, const Sched S, const Epi E) {
;     ...
;         for (int t = 0; t < nt; t += 2) {
;             const bool last = (t == nt - 2);
;             const char* a1 = cA + (size_t)(t + 1) * kstep;
;             const char* a2 = last ? nA : cA + (size_t)(t + 2) * kstep; const char* b2 = last ? nB : cB + (size_t)(t + 2) * kstep;
;     ...
;             PG8_LDA(At, 1, 1); PG8_STAGE(PG8_SB(1, 0), b3, voffB); PG8_STAGE(PG8_SB(1, 1), b3 + hstep, voffB); PG8_STAGE(PG8_SA(1, 0), a3, voffA);
;             PG8_WAIT_V(8); PG8_WAIT_L(0); PG8_BAR; PG8_MMA(1, 0, At, B0); PG8_MMA(1, 1, At, B1); PG8_BAR; PG8_SCHED;
	s_add_i32 s14, s20, s79
	v_lshl_add_u64 v[176:177], v[176:177], 0, s[12:13]
	s_mov_b32 m0, s14
	ds_read_b128 v[202:205], v170 offset:49152
	ds_read_b128 v[206:209], v170 offset:50176
	ds_read_b128 v[210:213], v170 offset:51200
	ds_read_b128 v[214:217], v170 offset:52224
	ds_read_b128 v[218:221], v170 offset:53248
	ds_read_b128 v[222:225], v170 offset:54272
	ds_read_b128 v[226:229], v170 offset:55296
	ds_read_b128 v[230:233], v170 offset:56320
	global_load_lds_dwordx4 v[176:177], off
	v_lshl_add_u64 v[176:177], v[234:235], 0, s[12:13]
	s_add_i32 m0, s14, 0x2000
	s_add_i32 s14, s21, s79
	global_load_lds_dwordx4 v[176:177], off
	v_lshl_add_u64 v[176:177], v[236:237], 0, s[12:13]
	s_mov_b32 m0, s14
	s_nop 0
	global_load_lds_dwordx4 v[176:177], off
	v_lshl_add_u64 v[176:177], v[238:239], 0, s[12:13]
	s_add_i32 m0, s14, 0x2000
	s_nop 0
	global_load_lds_dwordx4 v[176:177], off
	v_lshl_add_u64 v[176:177], v[240:241], 0, s[12:13]
	s_mov_b32 m0, s84
	s_nop 0
	global_load_lds_dwordx4 v[176:177], off
	v_lshl_add_u64 v[176:177], v[242:243], 0, s[12:13]
	s_mov_b32 m0, s85
	s_nop 0
	global_load_lds_dwordx4 v[176:177], off
	s_waitcnt vmcnt(8)
	s_waitcnt lgkmcnt(0)
	s_barrier
	s_setprio 1
	s_waitcnt lgkmcnt(0)
	v_mfma_f32_16x16x32_bf16 v[70:73], v[134:137], v[202:205], v[70:73]
	v_mfma_f32_16x16x32_bf16 v[66:69], v[142:145], v[202:205], v[66:69]
	v_mfma_f32_16x16x32_bf16 v[86:89], v[134:137], v[210:213], v[86:89]
	v_mfma_f32_16x16x32_bf16 v[82:85], v[142:145], v[210:213], v[82:85]
	v_mfma_f32_16x16x32_bf16 v[102:105], v[134:137], v[218:221], v[102:105]
	v_mfma_f32_16x16x32_bf16 v[98:101], v[142:145], v[218:221], v[98:101]
	v_mfma_f32_16x16x32_bf16 v[118:121], v[134:137], v[226:229], v[118:121]
	v_mfma_f32_16x16x32_bf16 v[114:117], v[142:145], v[226:229], v[114:117]
	v_mfma_f32_16x16x32_bf16 v[70:73], v[138:141], v[206:209], v[70:73]
	v_mfma_f32_16x16x32_bf16 v[66:69], v[158:161], v[206:209], v[66:69]
	v_mfma_f32_16x16x32_bf16 v[86:89], v[138:141], v[214:217], v[86:89]
	v_mfma_f32_16x16x32_bf16 v[82:85], v[158:161], v[214:217], v[82:85]
	v_mfma_f32_16x16x32_bf16 v[102:105], v[138:141], v[222:225], v[102:105]
	v_mfma_f32_16x16x32_bf16 v[98:101], v[158:161], v[222:225], v[98:101]
	v_mfma_f32_16x16x32_bf16 v[118:121], v[138:141], v[230:233], v[118:121]
	v_mfma_f32_16x16x32_bf16 v[114:117], v[158:161], v[230:233], v[114:117]
	s_setprio 0
	s_setprio 1
	v_mfma_f32_16x16x32_bf16 v[78:81], v[162:165], v[202:205], v[78:81]
	v_mfma_f32_16x16x32_bf16 v[74:77], v[182:185], v[202:205], v[74:77]
	v_mfma_f32_16x16x32_bf16 v[94:97], v[162:165], v[210:213], v[94:97]
	v_mfma_f32_16x16x32_bf16 v[90:93], v[182:185], v[210:213], v[90:93]
	v_mfma_f32_16x16x32_bf16 v[110:113], v[162:165], v[218:221], v[110:113]
	v_mfma_f32_16x16x32_bf16 v[106:109], v[182:185], v[218:221], v[106:109]
	v_mfma_f32_16x16x32_bf16 v[126:129], v[162:165], v[226:229], v[126:129]
	v_mfma_f32_16x16x32_bf16 v[122:125], v[182:185], v[226:229], v[122:125]
	v_mfma_f32_16x16x32_bf16 v[78:81], v[172:175], v[206:209], v[78:81]
	v_mfma_f32_16x16x32_bf16 v[74:77], v[198:201], v[206:209], v[74:77]
	v_mfma_f32_16x16x32_bf16 v[94:97], v[172:175], v[214:217], v[94:97]
	v_mfma_f32_16x16x32_bf16 v[90:93], v[198:201], v[214:217], v[90:93]
	v_mfma_f32_16x16x32_bf16 v[110:113], v[172:175], v[222:225], v[110:113]
	v_mfma_f32_16x16x32_bf16 v[106:109], v[198:201], v[222:225], v[106:109]
	v_mfma_f32_16x16x32_bf16 v[126:129], v[172:175], v[230:233], v[126:129]
	v_mfma_f32_16x16x32_bf16 v[122:125], v[198:201], v[230:233], v[122:125]
	s_setprio 0
	s_add_u32 s16, s16, 0x100
	s_addc_u32 s17, s17, 0
	v_lshl_add_u64 v[132:133], v[132:133], 0, s[30:31]
	v_lshl_add_u64 v[130:131], v[130:131], 0, s[30:31]
	s_cmp_ge_u32 s3, s88
	s_mov_b32 s14, s3
	s_barrier
	s_cbranch_scc0 .LBB0_416
	s_and_b64 vcc, exec, s[62:63]
	s_cbranch_vccz .LBB0_419
	s_barrier

; #define PG8_STAGE(bufoff, gbase, voff) do { _Pragma("unroll") for (int _i = 0; _i < 2; ++_i) \
;         __builtin_amdgcn_global_load_lds((const unsigned*)((const char*)(gbase) + (voff)[_i]), (PG8_LAS unsigned*)(lds + (bufoff) + ldsw + _i * 8192), 16, 0, 0); } while (0)
; #define PG8_LDA(dst, b, h) do { _Pragma("unroll") for (int m = 0; m < 4; ++m) _Pragma("unroll") for (int k = 0; k < 2; ++k) dst[m][k] = *(const PG8_LAS bf16x8*)(lds + PG8_SA(b, h) + aoff + m * 2048 + k * 1024); } while (0)
; #define PG8_LDB(dst, b, h) do { _Pragma("unroll") for (int n = 0; n < 2; ++n) _Pragma("unroll") for (int k = 0; k < 2; ++k) dst[n][k] = *(const PG8_LAS bf16x8*)(lds + PG8_SB(b, h) + boff + n * 2048 + k * 1024); } while (0)
; #define PG8_MMA(ai, bj, At, Bt) do { __builtin_amdgcn_s_setprio(1); _Pragma("unroll") for (int m = 0; m < 4; ++m) _Pragma("unroll") for (int n = 0; n < 2; ++n) _Pragma("unroll") for (int k = 0; k < 2; ++k) \
;         acc[ai][bj][m][n] = __builtin_amdgcn_mfma_f32_16x16x32_bf16(Bt[n][k], At[m][k], acc[ai][bj][m][n], 0, 0, 0); __builtin_amdgcn_s_setprio(0); } while (0)
; #define PG8_WAIT_V(n) asm volatile("s_waitcnt vmcnt(" #n ")" ::: "memory")
; #define PG8_WAIT_L(n) asm volatile("s_waitcnt lgkmcnt(" #n ")" ::: "memory")
; #define PG8_BAR __builtin_amdgcn_s_barrier()
; #define PG8_SCHED __builtin_amdgcn_sched_barrier(0)
; template <class Epi, class Sched, bool ALIGN_EPI = false, bool SP2 = false>
; __device__ __forceinline__ void gemm_phase(PG8_LAS unsigned char* lds, const Gemm g, const Sched S, const Epi E) {
;     ...
;             const bool last = (t == nt - 2);
;             const char* a1 = cA + (size_t)(t + 1) * kstep;
;             const char* a2 = last ? nA : cA + (size_t)(t + 2) * kstep; const char* b2 = last ? nB : cB + (size_t)(t + 2) * kstep;
;             const char* a3 = a2 + kstep; const char* b3 = b2 + kstep;
;             if (last && has_next) S.a_ready(nxt);
;             if constexpr (SP2) {
;             PG8_LDB(B0, 0, 0); PG8_LDB(B1, 0, 1); PG8_SCHED; PG8_LDA(At, 0, 0); PG8_STAGE(PG8_SA(1, 1), a1 + hstep, voffA);
;             PG8_WAIT_V(8); PG8_WAIT_L(0); PG8_BAR; PG8_MMA(0, 0, At, B0); PG8_MMA(0, 1, At, B1); PG8_BAR; PG8_SCHED;
;             PG8_LDA(At, 0, 1); PG8_STAGE(PG8_SB(0, 0), b2, voffB); PG8_STAGE(PG8_SB(0, 1), b2 + hstep, voffB); PG8_STAGE(PG8_SA(0, 0), a2, voffA);
.LBB0_538:
	s_add_i32 s3, s14, 2
	s_add_u32 s15, s68, s16
	s_addc_u32 s18, s69, s17
	s_add_u32 s20, s66, s16
	s_addc_u32 s21, s67, s17
	s_add_i32 s22, 0, 0x10000
	s_cmp_eq_u32 s81, s14
	s_cselect_b32 s19, s1, s18
	s_cselect_b32 s18, s0, s15
	v_add_u32_e32 v155, s22, v152
	s_cselect_b32 s15, s55, s21
	s_cselect_b32 s14, s54, s20
	s_add_i32 s20, 0, 0x14000
	ds_read_b128 v[146:149], v155
	ds_read_b128 v[156:159], v155 offset:1024
	ds_read_b128 v[160:163], v155 offset:2048
	ds_read_b128 v[164:167], v155 offset:3072
	v_add_u32_e32 v155, s20, v152
	ds_read_b128 v[168:171], v155
	ds_read_b128 v[172:175], v155 offset:1024
	ds_read_b128 v[182:185], v155 offset:2048
	ds_read_b128 v[198:201], v155 offset:3072
	v_lshl_add_u64 v[176:177], s[68:69], 0, v[144:145]
	s_add_i32 m0, s72, 0xc000
	ds_read_b128 v[202:205], v154
	ds_read_b128 v[206:209], v154 offset:1024
	ds_read_b128 v[210:213], v154 offset:2048
	ds_read_b128 v[214:217], v154 offset:3072
	ds_read_b128 v[218:221], v154 offset:4096
	ds_read_b128 v[222:225], v154 offset:5120
	ds_read_b128 v[226:229], v154 offset:6144
	ds_read_b128 v[230:233], v154 offset:7168
	global_load_lds_dwordx4 v[176:177], off
	v_lshl_add_u64 v[176:177], s[68:69], 0, v[142:143]
	s_add_i32 m0, s72, 0xe000
	s_nop 0
	global_load_lds_dwordx4 v[176:177], off
	s_waitcnt vmcnt(8)
	s_waitcnt lgkmcnt(0)
	s_barrier
	s_setprio 1
	s_waitcnt lgkmcnt(0)
	v_mfma_f32_16x16x32_bf16 v[62:65], v[146:149], v[202:205], v[62:65]
	v_mfma_f32_16x16x32_bf16 v[54:57], v[160:163], v[202:205], v[54:57]
	v_mfma_f32_16x16x32_bf16 v[14:17], v[146:149], v[210:213], v[14:17]
	v_mfma_f32_16x16x32_bf16 v[10:13], v[160:163], v[210:213], v[10:13]
	v_mfma_f32_16x16x32_bf16 v[30:33], v[146:149], v[218:221], v[30:33]
	v_mfma_f32_16x16x32_bf16 v[26:29], v[160:163], v[218:221], v[26:29]
	v_mfma_f32_16x16x32_bf16 v[46:49], v[146:149], v[226:229], v[46:49]
	v_mfma_f32_16x16x32_bf16 v[42:45], v[160:163], v[226:229], v[42:45]
	v_mfma_f32_16x16x32_bf16 v[62:65], v[156:159], v[206:209], v[62:65]
	v_mfma_f32_16x16x32_bf16 v[54:57], v[164:167], v[206:209], v[54:57]
	v_mfma_f32_16x16x32_bf16 v[14:17], v[156:159], v[214:217], v[14:17]
	v_mfma_f32_16x16x32_bf16 v[10:13], v[164:167], v[214:217], v[10:13]
	v_mfma_f32_16x16x32_bf16 v[30:33], v[156:159], v[222:225], v[30:33]
	v_mfma_f32_16x16x32_bf16 v[26:29], v[164:167], v[222:225], v[26:29]
	v_mfma_f32_16x16x32_bf16 v[46:49], v[156:159], v[230:233], v[46:49]
	v_mfma_f32_16x16x32_bf16 v[42:45], v[164:167], v[230:233], v[42:45]
	s_setprio 0
	s_setprio 1
	v_mfma_f32_16x16x32_bf16 v[6:9], v[168:171], v[202:205], v[6:9]
	v_mfma_f32_16x16x32_bf16 v[2:5], v[182:185], v[202:205], v[2:5]
	v_mfma_f32_16x16x32_bf16 v[22:25], v[168:171], v[210:213], v[22:25]
	v_mfma_f32_16x16x32_bf16 v[18:21], v[182:185], v[210:213], v[18:21]
	v_mfma_f32_16x16x32_bf16 v[38:41], v[168:171], v[218:221], v[38:41]
	v_mfma_f32_16x16x32_bf16 v[34:37], v[182:185], v[218:221], v[34:37]
	v_mfma_f32_16x16x32_bf16 v[58:61], v[168:171], v[226:229], v[58:61]
	v_mfma_f32_16x16x32_bf16 v[50:53], v[182:185], v[226:229], v[50:53]
	v_mfma_f32_16x16x32_bf16 v[6:9], v[172:175], v[206:209], v[6:9]
	v_mfma_f32_16x16x32_bf16 v[2:5], v[198:201], v[206:209], v[2:5]
	v_mfma_f32_16x16x32_bf16 v[22:25], v[172:175], v[214:217], v[22:25]
	v_mfma_f32_16x16x32_bf16 v[18:21], v[198:201], v[214:217], v[18:21]
	v_mfma_f32_16x16x32_bf16 v[38:41], v[172:175], v[222:225], v[38:41]
	v_mfma_f32_16x16x32_bf16 v[34:37], v[198:201], v[222:225], v[34:37]
	v_mfma_f32_16x16x32_bf16 v[58:61], v[172:175], v[230:233], v[58:61]
	v_mfma_f32_16x16x32_bf16 v[50:53], v[198:201], v[230:233], v[50:53]
	s_setprio 0
	s_barrier
	s_add_i32 s21, s22, s71
	v_lshl_add_u64 v[176:177], s[14:15], 0, v[0:1]
	s_mov_b32 m0, s21
	ds_read_b128 v[202:205], v154 offset:16384
	ds_read_b128 v[206:209], v154 offset:17408
	ds_read_b128 v[210:213], v154 offset:18432
	ds_read_b128 v[214:217], v154 offset:19456
	ds_read_b128 v[218:221], v154 offset:20480
	ds_read_b128 v[222:225], v154 offset:21504
	ds_read_b128 v[226:229], v154 offset:22528
	ds_read_b128 v[230:233], v154 offset:23552
	global_load_lds_dwordx4 v[176:177], off
	s_add_i32 m0, s21, 0x2000
	v_lshl_add_u64 v[234:235], s[14:15], 0, v[134:135]
	s_add_u32 s14, s14, s28
	s_addc_u32 s15, s15, 0
	s_add_i32 s20, s20, s71
	global_load_lds_dwordx4 v[234:235], off
	v_lshl_add_u64 v[236:237], s[14:15], 0, v[0:1]
	s_mov_b32 m0, s20
	v_lshl_add_u64 v[238:239], s[14:15], 0, v[134:135]
	global_load_lds_dwordx4 v[236:237], off
	s_add_i32 m0, s20, 0x2000
	v_lshl_add_u64 v[240:241], s[18:19], 0, v[130:131]
	global_load_lds_dwordx4 v[238:239], off
	s_mov_b32 m0, s72
	v_lshl_add_u64 v[242:243], s[18:19], 0, v[132:133]
	global_load_lds_dwordx4 v[240:241], off
	s_mov_b32 m0, s73
	s_nop 0
	global_load_lds_dwordx4 v[242:243], off
	s_waitcnt vmcnt(8)
	s_waitcnt lgkmcnt(0)
	s_barrier
; #define PG8_STAGE(bufoff, gbase, voff) do { _Pragma("unroll") for (int _i = 0; _i < 2; ++_i) \
;         __builtin_amdgcn_global_load_lds((const unsigned*)((const char*)(gbase) + (voff)[_i]), (PG8_LAS unsigned*)(lds + (bufoff) + ldsw + _i * 8192), 16, 0, 0); } while (0)
; #define PG8_LDA(dst, b, h) do { _Pragma("unroll") for (int m = 0; m < 4; ++m) _Pragma("unroll") for (int k = 0; k < 2; ++k) dst[m][k] = *(const PG8_LAS bf16x8*)(lds + PG8_SA(b, h) + aoff + m * 2048 + k * 1024); } while (0)
; #define PG8_LDB(dst, b, h) do { _Pragma("unroll") for (int n = 0; n < 2; ++n) _Pragma("unroll") for (int k = 0; k < 2; ++k) dst[n][k] = *(const PG8_LAS bf16x8*)(lds + PG8_SB(b, h) + boff + n * 2048 + k * 1024); } while (0)
; #define PG8_MMA(ai, bj, At, Bt) do { __builtin_amdgcn_s_setprio(1); _Pragma("unroll") for (int m = 0; m < 4; ++m) _Pragma("unroll") for (int n = 0; n < 2; ++n) _Pragma("unroll") for (int k = 0; k < 2; ++k) \
;         acc[ai][bj][m][n] = __builtin_amdgcn_mfma_f32_16x16x32_bf16(Bt[n][k], At[m][k], acc[ai][bj][m][n], 0, 0, 0); __builtin_amdgcn_s_setprio(0); } while (0)
; #define PG8_WAIT_V(n) asm volatile("s_waitcnt vmcnt(" #n ")" ::: "memory")
; #define PG8_WAIT_L(n) asm volatile("s_waitcnt lgkmcnt(" #n ")" ::: "memory")
; #define PG8_BAR __builtin_amdgcn_s_barrier()
; #define PG8_SCHED __builtin_amdgcn_sched_barrier(0)
; template <class Epi, class Sched, bool ALIGN_EPI = false, bool SP2 = false>
; __device__ __forceinline__ void gemm_phase(PG8_LAS unsigned char* lds, const Gemm g, const Sched S, const Epi E) {
;     ...
;             PG8_WAIT_V(8); PG8_WAIT_L(0); PG8_BAR; PG8_MMA(1, 0, At, B0); PG8_MMA(1, 1, At, B1); PG8_BAR; PG8_SCHED;
;             PG8_LDB(B0, 1, 0); PG8_LDB(B1, 1, 1); PG8_SCHED; PG8_LDA(At, 1, 0); PG8_STAGE(PG8_SA(0, 1), a2 + hstep, voffA);
;             PG8_WAIT_V(8); PG8_WAIT_L(0); PG8_BAR; PG8_MMA(0, 0, At, B0); PG8_MMA(0, 1, At, B1); PG8_BAR; PG8_SCHED;
	s_setprio 1
	s_waitcnt lgkmcnt(0)
	v_mfma_f32_16x16x32_bf16 v[70:73], v[146:149], v[202:205], v[70:73]
	v_mfma_f32_16x16x32_bf16 v[66:69], v[160:163], v[202:205], v[66:69]
	v_mfma_f32_16x16x32_bf16 v[86:89], v[146:149], v[210:213], v[86:89]
	v_mfma_f32_16x16x32_bf16 v[82:85], v[160:163], v[210:213], v[82:85]
	v_mfma_f32_16x16x32_bf16 v[102:105], v[146:149], v[218:221], v[102:105]
	v_mfma_f32_16x16x32_bf16 v[98:101], v[160:163], v[218:221], v[98:101]
	v_mfma_f32_16x16x32_bf16 v[118:121], v[146:149], v[226:229], v[118:121]
	v_mfma_f32_16x16x32_bf16 v[114:117], v[160:163], v[226:229], v[114:117]
	v_mfma_f32_16x16x32_bf16 v[70:73], v[156:159], v[206:209], v[70:73]
	v_mfma_f32_16x16x32_bf16 v[66:69], v[164:167], v[206:209], v[66:69]
	v_mfma_f32_16x16x32_bf16 v[86:89], v[156:159], v[214:217], v[86:89]
	v_mfma_f32_16x16x32_bf16 v[82:85], v[164:167], v[214:217], v[82:85]
	v_mfma_f32_16x16x32_bf16 v[102:105], v[156:159], v[222:225], v[102:105]
	v_mfma_f32_16x16x32_bf16 v[98:101], v[164:167], v[222:225], v[98:101]
	v_mfma_f32_16x16x32_bf16 v[118:121], v[156:159], v[230:233], v[118:121]
	v_mfma_f32_16x16x32_bf16 v[114:117], v[164:167], v[230:233], v[114:117]
	s_setprio 0
	s_setprio 1
	v_mfma_f32_16x16x32_bf16 v[78:81], v[168:171], v[202:205], v[78:81]
	v_mfma_f32_16x16x32_bf16 v[74:77], v[182:185], v[202:205], v[74:77]
	v_mfma_f32_16x16x32_bf16 v[94:97], v[168:171], v[210:213], v[94:97]
	v_mfma_f32_16x16x32_bf16 v[90:93], v[182:185], v[210:213], v[90:93]
	v_mfma_f32_16x16x32_bf16 v[110:113], v[168:171], v[218:221], v[110:113]
	v_mfma_f32_16x16x32_bf16 v[106:109], v[182:185], v[218:221], v[106:109]
	v_mfma_f32_16x16x32_bf16 v[126:129], v[168:171], v[226:229], v[126:129]
	v_mfma_f32_16x16x32_bf16 v[122:125], v[182:185], v[226:229], v[122:125]
	v_mfma_f32_16x16x32_bf16 v[78:81], v[172:175], v[206:209], v[78:81]
	v_mfma_f32_16x16x32_bf16 v[74:77], v[198:201], v[206:209], v[74:77]
	v_mfma_f32_16x16x32_bf16 v[94:97], v[172:175], v[214:217], v[94:97]
	v_mfma_f32_16x16x32_bf16 v[90:93], v[198:201], v[214:217], v[90:93]
	v_mfma_f32_16x16x32_bf16 v[110:113], v[172:175], v[222:225], v[110:113]
	v_mfma_f32_16x16x32_bf16 v[106:109], v[198:201], v[222:225], v[106:109]
	v_mfma_f32_16x16x32_bf16 v[126:129], v[172:175], v[230:233], v[126:129]
	v_mfma_f32_16x16x32_bf16 v[122:125], v[198:201], v[230:233], v[122:125]
	s_setprio 0
	s_barrier
	s_add_i32 s20, 0, 0x18000
	v_add_u32_e32 v155, s20, v152
	s_add_i32 s21, 0, 0x1c000
	ds_read_b128 v[146:149], v155
	ds_read_b128 v[156:159], v155 offset:1024
	ds_read_b128 v[160:163], v155 offset:2048
	ds_read_b128 v[164:167], v155 offset:3072
	v_add_u32_e32 v155, s21, v152
	ds_read_b128 v[168:171], v155
	ds_read_b128 v[172:175], v155 offset:1024
	ds_read_b128 v[182:185], v155 offset:2048
	ds_read_b128 v[198:201], v155 offset:3072
	s_add_u32 s14, s18, s28
	s_addc_u32 s15, s19, 0
	s_mov_b32 m0, s74
	v_lshl_add_u64 v[244:245], s[14:15], 0, v[130:131]
	ds_read_b128 v[202:205], v154 offset:32768
	ds_read_b128 v[206:209], v154 offset:33792
	ds_read_b128 v[210:213], v154 offset:34816
	ds_read_b128 v[214:217], v154 offset:35840
	ds_read_b128 v[218:221], v154 offset:36864
	ds_read_b128 v[222:225], v154 offset:37888
	ds_read_b128 v[226:229], v154 offset:38912
	ds_read_b128 v[230:233], v154 offset:39936
	global_load_lds_dwordx4 v[244:245], off
	v_lshl_add_u64 v[244:245], s[14:15], 0, v[132:133]
	s_mov_b32 m0, s75
	s_nop 0
	global_load_lds_dwordx4 v[244:245], off
	s_waitcnt vmcnt(8)
	s_waitcnt lgkmcnt(0)
	s_barrier
	s_setprio 1
	s_waitcnt lgkmcnt(0)
	v_mfma_f32_16x16x32_bf16 v[62:65], v[146:149], v[202:205], v[62:65]
	v_mfma_f32_16x16x32_bf16 v[54:57], v[160:163], v[202:205], v[54:57]
	v_mfma_f32_16x16x32_bf16 v[14:17], v[146:149], v[210:213], v[14:17]
	v_mfma_f32_16x16x32_bf16 v[10:13], v[160:163], v[210:213], v[10:13]
	v_mfma_f32_16x16x32_bf16 v[30:33], v[146:149], v[218:221], v[30:33]
	v_mfma_f32_16x16x32_bf16 v[26:29], v[160:163], v[218:221], v[26:29]
	v_mfma_f32_16x16x32_bf16 v[46:49], v[146:149], v[226:229], v[46:49]
	v_mfma_f32_16x16x32_bf16 v[42:45], v[160:163], v[226:229], v[42:45]
	v_mfma_f32_16x16x32_bf16 v[62:65], v[156:159], v[206:209], v[62:65]
	v_mfma_f32_16x16x32_bf16 v[54:57], v[164:167], v[206:209], v[54:57]
	v_mfma_f32_16x16x32_bf16 v[14:17], v[156:159], v[214:217], v[14:17]
	v_mfma_f32_16x16x32_bf16 v[10:13], v[164:167], v[214:217], v[10:13]
	v_mfma_f32_16x16x32_bf16 v[30:33], v[156:159], v[222:225], v[30:33]
	v_mfma_f32_16x16x32_bf16 v[26:29], v[164:167], v[222:225], v[26:29]
	v_mfma_f32_16x16x32_bf16 v[46:49], v[156:159], v[230:233], v[46:49]
	v_mfma_f32_16x16x32_bf16 v[42:45], v[164:167], v[230:233], v[42:45]
	s_setprio 0
	s_setprio 1
	v_mfma_f32_16x16x32_bf16 v[6:9], v[168:171], v[202:205], v[6:9]
	v_mfma_f32_16x16x32_bf16 v[2:5], v[182:185], v[202:205], v[2:5]
	v_mfma_f32_16x16x32_bf16 v[22:25], v[168:171], v[210:213], v[22:25]
	v_mfma_f32_16x16x32_bf16 v[18:21], v[182:185], v[210:213], v[18:21]
	v_mfma_f32_16x16x32_bf16 v[38:41], v[168:171], v[218:221], v[38:41]
	v_mfma_f32_16x16x32_bf16 v[34:37], v[182:185], v[218:221], v[34:37]
	v_mfma_f32_16x16x32_bf16 v[58:61], v[168:171], v[226:229], v[58:61]
	v_mfma_f32_16x16x32_bf16 v[50:53], v[182:185], v[226:229], v[50:53]
	v_mfma_f32_16x16x32_bf16 v[6:9], v[172:175], v[206:209], v[6:9]
	v_mfma_f32_16x16x32_bf16 v[2:5], v[198:201], v[206:209], v[2:5]
	v_mfma_f32_16x16x32_bf16 v[22:25], v[172:175], v[214:217], v[22:25]
	v_mfma_f32_16x16x32_bf16 v[18:21], v[198:201], v[214:217], v[18:21]
	v_mfma_f32_16x16x32_bf16 v[38:41], v[172:175], v[222:225], v[38:41]
	v_mfma_f32_16x16x32_bf16 v[34:37], v[198:201], v[222:225], v[34:37]
	v_mfma_f32_16x16x32_bf16 v[58:61], v[172:175], v[230:233], v[58:61]
	v_mfma_f32_16x16x32_bf16 v[50:53], v[198:201], v[230:233], v[50:53]
	s_setprio 0
	s_barrier
; #define PG8_STAGE(bufoff, gbase, voff) do { _Pragma("unroll") for (int _i = 0; _i < 2; ++_i) \
;         __builtin_amdgcn_global_load_lds((const unsigned*)((const char*)(gbase) + (voff)[_i]), (PG8_LAS unsigned*)(lds + (bufoff) + ldsw + _i * 8192), 16, 0, 0); } while (0)
; #define PG8_LDA(dst, b, h) do { _Pragma("unroll") for (int m = 0; m < 4; ++m) _Pragma("unroll") for (int k = 0; k < 2; ++k) dst[m][k] = *(const PG8_LAS bf16x8*)(lds + PG8_SA(b, h) + aoff + m * 2048 + k * 1024); } while (0)
; #define PG8_MMA(ai, bj, At, Bt) do { __builtin_amdgcn_s_setprio(1); _Pragma("unroll") for (int m = 0; m < 4; ++m) _Pragma("unroll") for (int n = 0; n < 2; ++n) _Pragma("unroll") for (int k = 0; k < 2; ++k) \
;         acc[ai][bj][m][n] = __builtin_amdgcn_mfma_f32_16x16x32_bf16(Bt[n][k], At[m][k], acc[ai][bj][m][n], 0, 0, 0); __builtin_amdgcn_s_setprio(0); } while (0)
; #define PG8_WAIT_V(n) asm volatile("s_waitcnt vmcnt(" #n ")" ::: "memory")
; #define PG8_WAIT_L(n) asm volatile("s_waitcnt lgkmcnt(" #n ")" ::: "memory")
; #define PG8_BAR __builtin_amdgcn_s_barrier()
; #define PG8_SCHED __builtin_amdgcn_sched_barrier(0)
; template <class Epi, class Sched, bool ALIGN_EPI = false, bool SP2 = false>
; __device__ __forceinline__ void gemm_phase(PG8_LAS unsigned char* lds, const Gemm g, const Sched S, const Epi E) {
;     ...
;         for (int t = 0; t < nt; t += 2) {
;             const bool last = (t == nt - 2);
;             const char* a1 = cA + (size_t)(t + 1) * kstep;
;             const char* a2 = last ? nA : cA + (size_t)(t + 2) * kstep; const char* b2 = last ? nB : cB + (size_t)(t + 2) * kstep;
;     ...
;             PG8_LDA(At, 1, 1); PG8_STAGE(PG8_SB(1, 0), b3, voffB); PG8_STAGE(PG8_SB(1, 1), b3 + hstep, voffB); PG8_STAGE(PG8_SA(1, 0), a3, voffA);
;             PG8_WAIT_V(8); PG8_WAIT_L(0); PG8_BAR; PG8_MMA(1, 0, At, B0); PG8_MMA(1, 1, At, B1); PG8_BAR; PG8_SCHED;
	s_add_i32 s14, s20, s71
	v_lshl_add_u64 v[176:177], v[176:177], 0, s[12:13]
	s_mov_b32 m0, s14
	ds_read_b128 v[202:205], v154 offset:49152
	ds_read_b128 v[206:209], v154 offset:50176
	ds_read_b128 v[210:213], v154 offset:51200
	ds_read_b128 v[214:217], v154 offset:52224
	ds_read_b128 v[218:221], v154 offset:53248
	ds_read_b128 v[222:225], v154 offset:54272
	ds_read_b128 v[226:229], v154 offset:55296
	ds_read_b128 v[230:233], v154 offset:56320
	global_load_lds_dwordx4 v[176:177], off
	v_lshl_add_u64 v[176:177], v[234:235], 0, s[12:13]
	s_add_i32 m0, s14, 0x2000
	s_add_i32 s14, s21, s71
	global_load_lds_dwordx4 v[176:177], off
	v_lshl_add_u64 v[176:177], v[236:237], 0, s[12:13]
	s_mov_b32 m0, s14
	s_nop 0
	global_load_lds_dwordx4 v[176:177], off
	v_lshl_add_u64 v[176:177], v[238:239], 0, s[12:13]
	s_add_i32 m0, s14, 0x2000
	s_nop 0
	global_load_lds_dwordx4 v[176:177], off
	v_lshl_add_u64 v[176:177], v[240:241], 0, s[12:13]
	s_mov_b32 m0, s77
	s_nop 0
	global_load_lds_dwordx4 v[176:177], off
	v_lshl_add_u64 v[176:177], v[242:243], 0, s[12:13]
	s_mov_b32 m0, s78
	s_nop 0
	global_load_lds_dwordx4 v[176:177], off
	s_waitcnt vmcnt(8)
	s_waitcnt lgkmcnt(0)
	s_barrier
	s_setprio 1
	s_waitcnt lgkmcnt(0)
	v_mfma_f32_16x16x32_bf16 v[70:73], v[146:149], v[202:205], v[70:73]
	v_mfma_f32_16x16x32_bf16 v[66:69], v[160:163], v[202:205], v[66:69]
	v_mfma_f32_16x16x32_bf16 v[86:89], v[146:149], v[210:213], v[86:89]
	v_mfma_f32_16x16x32_bf16 v[82:85], v[160:163], v[210:213], v[82:85]
	v_mfma_f32_16x16x32_bf16 v[102:105], v[146:149], v[218:221], v[102:105]
	v_mfma_f32_16x16x32_bf16 v[98:101], v[160:163], v[218:221], v[98:101]
	v_mfma_f32_16x16x32_bf16 v[118:121], v[146:149], v[226:229], v[118:121]
	v_mfma_f32_16x16x32_bf16 v[114:117], v[160:163], v[226:229], v[114:117]
	v_mfma_f32_16x16x32_bf16 v[70:73], v[156:159], v[206:209], v[70:73]
	v_mfma_f32_16x16x32_bf16 v[66:69], v[164:167], v[206:209], v[66:69]
	v_mfma_f32_16x16x32_bf16 v[86:89], v[156:159], v[214:217], v[86:89]
	v_mfma_f32_16x16x32_bf16 v[82:85], v[164:167], v[214:217], v[82:85]
	v_mfma_f32_16x16x32_bf16 v[102:105], v[156:159], v[222:225], v[102:105]
	v_mfma_f32_16x16x32_bf16 v[98:101], v[164:167], v[222:225], v[98:101]
	v_mfma_f32_16x16x32_bf16 v[118:121], v[156:159], v[230:233], v[118:121]
	v_mfma_f32_16x16x32_bf16 v[114:117], v[164:167], v[230:233], v[114:117]
	s_setprio 0
	s_setprio 1
	v_mfma_f32_16x16x32_bf16 v[78:81], v[168:171], v[202:205], v[78:81]
	v_mfma_f32_16x16x32_bf16 v[74:77], v[182:185], v[202:205], v[74:77]
	v_mfma_f32_16x16x32_bf16 v[94:97], v[168:171], v[210:213], v[94:97]
	v_mfma_f32_16x16x32_bf16 v[90:93], v[182:185], v[210:213], v[90:93]
	v_mfma_f32_16x16x32_bf16 v[110:113], v[168:171], v[218:221], v[110:113]
	v_mfma_f32_16x16x32_bf16 v[106:109], v[182:185], v[218:221], v[106:109]
	v_mfma_f32_16x16x32_bf16 v[126:129], v[168:171], v[226:229], v[126:129]
	v_mfma_f32_16x16x32_bf16 v[122:125], v[182:185], v[226:229], v[122:125]
	v_mfma_f32_16x16x32_bf16 v[78:81], v[172:175], v[206:209], v[78:81]
	v_mfma_f32_16x16x32_bf16 v[74:77], v[198:201], v[206:209], v[74:77]
	v_mfma_f32_16x16x32_bf16 v[94:97], v[172:175], v[214:217], v[94:97]
	v_mfma_f32_16x16x32_bf16 v[90:93], v[198:201], v[214:217], v[90:93]
	v_mfma_f32_16x16x32_bf16 v[110:113], v[172:175], v[222:225], v[110:113]
	v_mfma_f32_16x16x32_bf16 v[106:109], v[198:201], v[222:225], v[106:109]
	v_mfma_f32_16x16x32_bf16 v[126:129], v[172:175], v[230:233], v[126:129]
	v_mfma_f32_16x16x32_bf16 v[122:125], v[198:201], v[230:233], v[122:125]
	s_setprio 0
	s_add_u32 s16, s16, 0x100
	s_addc_u32 s17, s17, 0
	v_lshl_add_u64 v[144:145], v[144:145], 0, s[88:89]
	v_lshl_add_u64 v[142:143], v[142:143], 0, s[88:89]
	s_cmp_ge_u32 s3, s76
	s_mov_b32 s14, s3
	s_barrier
	s_cbranch_scc0 .LBB0_538
	s_and_b64 vcc, exec, s[62:63]
	s_cbranch_vccz .LBB0_541
	s_barrier
